# v08 (split ds_read2_b64 in scan jobs) + la_job decay-stage LDS reads pipelined + lru_job: global loads, gate-stage LDS reads hoisted across exec diamonds
# speedup vs baseline: 1.0076x; 1.0063x over previous
.LBB0_711:
	s_nop 7
	v_cndmask_b32_e64 v1, v138, 0, s[48:49]
	v_cndmask_b32_e64 v35, v139, 0, s[50:51]
	v_cndmask_b32_e64 v37, v140, 0, s[52:53]
	v_cndmask_b32_e64 v138, v141, 0, s[54:55]
	v_cvt_pk_bf16_f32 v36, v1, v35
	v_cvt_pk_bf16_f32 v37, v37, v138
	ds_write_b64 v213, v[36:37]
	ds_read_b128 v[102:105], v155
	ds_read_b128 v[106:109], v180
	ds_read_b64 v[110:111], v157
	ds_read_b64 v[112:113], v157 offset:32
	s_nop 0
	s_nop 0
	v_add_u32_e32 v1, 0x2000, v157
	ds_read_b64 v[114:115], v1 offset:256
	ds_read_b64 v[116:117], v1 offset:288
	v_add_u32_e32 v35, 0x4000, v157
	ds_read_b64 v[118:119], v35 offset:512
	ds_read_b64 v[120:121], v35 offset:544
	v_add_u32_e32 v246, 0x6000, v157
	ds_read_b64 v[122:123], v246 offset:768
	ds_read_b64 v[124:125], v246 offset:800
	s_waitcnt lgkmcnt(11)
	s_waitcnt lgkmcnt(9)
	v_pk_mul_f32 v[36:37], v[4:5], v[104:105]
	ds_read_b128 v[126:129], v181
	v_pk_mul_f32 v[138:139], v[2:3], v[102:103]
	s_waitcnt lgkmcnt(9)
	v_pk_mul_f32 v[140:141], v[10:11], v[106:107]
	ds_read_b128 v[102:105], v182
	v_cvt_pk_bf16_f32 v138, v138, v139
	v_cvt_pk_bf16_f32 v139, v36, v37
	v_pk_mul_f32 v[36:37], v[12:13], v[108:109]
	v_cvt_pk_bf16_f32 v140, v140, v141
	v_cvt_pk_bf16_f32 v141, v36, v37
	s_nop 0
	s_nop 0
	s_nop 0
	s_nop 0
	s_nop 0
	s_waitcnt lgkmcnt(8)
	v_mfma_f32_16x16x32_bf16 v[142:145], v[138:141], v[110:113], 0
	ds_read_b64 v[106:107], v157 offset:64
	ds_read_b64 v[108:109], v157 offset:96
	s_andn2_b64 vcc, exec, s[22:23]
	s_waitcnt lgkmcnt(8)
	v_mfma_f32_16x16x32_bf16 v[146:149], v[138:141], v[114:117], 0
	ds_read_b64 v[110:111], v1 offset:320
	ds_read_b64 v[112:113], v1 offset:352
	s_waitcnt lgkmcnt(8)
	v_mfma_f32_16x16x32_bf16 v[150:153], v[138:141], v[118:121], 0
	ds_read_b64 v[114:115], v35 offset:576
	ds_read_b64 v[116:117], v35 offset:608
	s_waitcnt lgkmcnt(8)
	v_mfma_f32_16x16x32_bf16 v[138:141], v[138:141], v[122:125], 0
	ds_read_b64 v[118:119], v246 offset:832
	ds_read_b64 v[120:121], v246 offset:864
	s_nop 0
	s_nop 0
	s_nop 0
	s_waitcnt lgkmcnt(9)
	v_pk_mul_f32 v[36:37], v[8:9], v[128:129]
	ds_read_b128 v[122:125], v183
	v_pk_mul_f32 v[234:235], v[6:7], v[126:127]
	s_waitcnt lgkmcnt(9)
	v_pk_mul_f32 v[236:237], v[14:15], v[102:103]
	ds_read_b128 v[126:129], v184
	v_cvt_pk_bf16_f32 v234, v234, v235
	v_cvt_pk_bf16_f32 v235, v36, v37
	v_pk_mul_f32 v[36:37], v[16:17], v[104:105]
	v_cvt_pk_bf16_f32 v236, v236, v237
	v_cvt_pk_bf16_f32 v237, v36, v37
	s_nop 0
	s_nop 0
	s_waitcnt lgkmcnt(8)
	v_mfma_f32_16x16x32_bf16 v[142:145], v[234:237], v[106:109], v[142:145]
	ds_read_b64 v[102:103], v157 offset:128
	ds_read_b64 v[104:105], v157 offset:160
	s_nop 0
	s_nop 0
	s_waitcnt lgkmcnt(8)
	v_mfma_f32_16x16x32_bf16 v[146:149], v[234:237], v[110:113], v[146:149]
	ds_read_b64 v[106:107], v1 offset:384
	ds_read_b64 v[108:109], v1 offset:416
	s_nop 0
	s_nop 0
	s_waitcnt lgkmcnt(8)
	v_mfma_f32_16x16x32_bf16 v[150:153], v[234:237], v[114:117], v[150:153]
	ds_read_b64 v[110:111], v35 offset:640
	ds_read_b64 v[112:113], v35 offset:672
	s_nop 0
	s_nop 0
	s_waitcnt lgkmcnt(8)
	v_mfma_f32_16x16x32_bf16 v[138:141], v[234:237], v[118:121], v[138:141]
	ds_read_b64 v[114:115], v246 offset:896
	ds_read_b64 v[116:117], v246 offset:928
	s_nop 0
	s_nop 0
	s_nop 0
	s_waitcnt lgkmcnt(9)
	v_pk_mul_f32 v[36:37], v[20:21], v[124:125]
	ds_read_b128 v[118:121], v185
	v_pk_mul_f32 v[234:235], v[18:19], v[122:123]
	s_waitcnt lgkmcnt(9)
	v_pk_mul_f32 v[236:237], v[22:23], v[126:127]
	ds_read_b128 v[122:125], v186
	v_cvt_pk_bf16_f32 v234, v234, v235
	v_cvt_pk_bf16_f32 v235, v36, v37
	v_pk_mul_f32 v[36:37], v[24:25], v[128:129]
	v_cvt_pk_bf16_f32 v236, v236, v237
	v_cvt_pk_bf16_f32 v237, v36, v37
	s_nop 0
	s_nop 0
	s_waitcnt lgkmcnt(8)
	v_mfma_f32_16x16x32_bf16 v[142:145], v[234:237], v[102:105], v[142:145]
	ds_read_b64 v[102:103], v157 offset:192
	ds_read_b64 v[104:105], v157 offset:224
	s_nop 0
	s_nop 0
	s_waitcnt lgkmcnt(8)
	v_mfma_f32_16x16x32_bf16 v[146:149], v[234:237], v[106:109], v[146:149]
	ds_read_b64 v[106:107], v1 offset:448
	ds_read_b64 v[108:109], v1 offset:480
	s_nop 0
	s_nop 0
	s_waitcnt lgkmcnt(8)
	v_mfma_f32_16x16x32_bf16 v[150:153], v[234:237], v[110:113], v[150:153]
	ds_read_b64 v[110:111], v35 offset:704
	ds_read_b64 v[112:113], v35 offset:736
	s_nop 0
	s_nop 0
	s_waitcnt lgkmcnt(8)
	v_mfma_f32_16x16x32_bf16 v[138:141], v[234:237], v[114:117], v[138:141]
	ds_read_b64 v[114:115], v246 offset:960
	ds_read_b64 v[116:117], v246 offset:992
	s_nop 0
	s_nop 0
	s_nop 0
	s_waitcnt lgkmcnt(9)
	v_pk_mul_f32 v[36:37], v[28:29], v[120:121]
	ds_read_b128 v[126:129], v187
	v_pk_mul_f32 v[234:235], v[26:27], v[118:119]
	s_waitcnt lgkmcnt(9)
	v_pk_mul_f32 v[236:237], v[30:31], v[122:123]
	ds_read_b128 v[118:121], v188
	v_cvt_pk_bf16_f32 v234, v234, v235
	v_cvt_pk_bf16_f32 v235, v36, v37
	v_pk_mul_f32 v[36:37], v[32:33], v[124:125]
	v_cvt_pk_bf16_f32 v236, v236, v237
	v_cvt_pk_bf16_f32 v237, v36, v37
	s_nop 0
	s_nop 0
	s_waitcnt lgkmcnt(8)
	v_mfma_f32_16x16x32_bf16 v[142:145], v[234:237], v[102:105], v[142:145]
	ds_read_b64 v[102:103], v157 offset:256
	ds_read_b64 v[104:105], v157 offset:288
	s_nop 0
	s_nop 0
	s_waitcnt lgkmcnt(8)
	v_mfma_f32_16x16x32_bf16 v[146:149], v[234:237], v[106:109], v[146:149]
	ds_read_b64 v[106:107], v1 offset:512
	ds_read_b64 v[108:109], v1 offset:544
	s_nop 0
	s_nop 0
	s_waitcnt lgkmcnt(8)
	v_mfma_f32_16x16x32_bf16 v[150:153], v[234:237], v[110:113], v[150:153]
	ds_read_b64 v[110:111], v35 offset:768
	ds_read_b64 v[112:113], v35 offset:800
	s_nop 0
	s_nop 0
	s_waitcnt lgkmcnt(8)
	v_mfma_f32_16x16x32_bf16 v[138:141], v[234:237], v[114:117], v[138:141]
	ds_read_b64 v[114:115], v246 offset:1024
	ds_read_b64 v[116:117], v246 offset:1056
	s_nop 0
	s_nop 0
	s_nop 0
	s_waitcnt lgkmcnt(9)
	v_pk_mul_f32 v[36:37], v[40:41], v[128:129]
	ds_read_b128 v[122:125], v189
	v_pk_mul_f32 v[234:235], v[38:39], v[126:127]
	s_waitcnt lgkmcnt(9)
	v_pk_mul_f32 v[236:237], v[42:43], v[118:119]
	ds_read_b128 v[126:129], v190
	v_cvt_pk_bf16_f32 v234, v234, v235
	v_cvt_pk_bf16_f32 v235, v36, v37
	v_pk_mul_f32 v[36:37], v[44:45], v[120:121]
	v_cvt_pk_bf16_f32 v236, v236, v237
	v_cvt_pk_bf16_f32 v237, v36, v37
	s_nop 0
	s_nop 0
	s_waitcnt lgkmcnt(8)
	v_mfma_f32_16x16x32_bf16 v[142:145], v[234:237], v[102:105], v[142:145]
	ds_read_b64 v[102:103], v157 offset:320
	ds_read_b64 v[104:105], v157 offset:352
	s_nop 0
	s_nop 0
	s_waitcnt lgkmcnt(8)
	v_mfma_f32_16x16x32_bf16 v[146:149], v[234:237], v[106:109], v[146:149]
	ds_read_b64 v[106:107], v1 offset:576
	ds_read_b64 v[108:109], v1 offset:608
	s_nop 0
	s_nop 0
	s_waitcnt lgkmcnt(8)
	v_mfma_f32_16x16x32_bf16 v[150:153], v[234:237], v[110:113], v[150:153]
	ds_read_b64 v[110:111], v35 offset:832
	ds_read_b64 v[112:113], v35 offset:864
	s_nop 0
	s_nop 0
	s_waitcnt lgkmcnt(8)
	v_mfma_f32_16x16x32_bf16 v[138:141], v[234:237], v[114:117], v[138:141]
	ds_read_b64 v[114:115], v246 offset:1088
	ds_read_b64 v[116:117], v246 offset:1120
	s_nop 0
	s_nop 0
	s_nop 0
	s_waitcnt lgkmcnt(9)
	v_pk_mul_f32 v[36:37], v[48:49], v[124:125]
	ds_read_b128 v[118:121], v191
	v_pk_mul_f32 v[234:235], v[46:47], v[122:123]
	s_waitcnt lgkmcnt(9)
	v_pk_mul_f32 v[236:237], v[50:51], v[126:127]
	ds_read_b128 v[122:125], v192
	v_cvt_pk_bf16_f32 v234, v234, v235
	v_cvt_pk_bf16_f32 v235, v36, v37
	v_pk_mul_f32 v[36:37], v[52:53], v[128:129]
	v_cvt_pk_bf16_f32 v236, v236, v237
	v_cvt_pk_bf16_f32 v237, v36, v37
	s_nop 0
	s_nop 0
	s_waitcnt lgkmcnt(8)
	v_mfma_f32_16x16x32_bf16 v[142:145], v[234:237], v[102:105], v[142:145]
	ds_read_b64 v[102:103], v157 offset:384
	ds_read_b64 v[104:105], v157 offset:416
	s_nop 0
	s_nop 0
	s_waitcnt lgkmcnt(8)
	v_mfma_f32_16x16x32_bf16 v[146:149], v[234:237], v[106:109], v[146:149]
	ds_read_b64 v[106:107], v1 offset:640
	ds_read_b64 v[108:109], v1 offset:672
	s_nop 0
	s_nop 0
	s_waitcnt lgkmcnt(8)
	v_mfma_f32_16x16x32_bf16 v[150:153], v[234:237], v[110:113], v[150:153]
	ds_read_b64 v[110:111], v35 offset:896
	ds_read_b64 v[112:113], v35 offset:928
	s_nop 0
	s_nop 0
	s_waitcnt lgkmcnt(8)
	v_mfma_f32_16x16x32_bf16 v[138:141], v[234:237], v[114:117], v[138:141]
	ds_read_b64 v[114:115], v246 offset:1152
	ds_read_b64 v[116:117], v246 offset:1184
	s_nop 0
	s_nop 0
	s_nop 0
	s_waitcnt lgkmcnt(9)
	v_pk_mul_f32 v[36:37], v[56:57], v[120:121]
	ds_read_b128 v[126:129], v193
	v_pk_mul_f32 v[234:235], v[54:55], v[118:119]
	s_waitcnt lgkmcnt(9)
	v_pk_mul_f32 v[236:237], v[58:59], v[122:123]
	ds_read_b128 v[118:121], v194
	v_cvt_pk_bf16_f32 v234, v234, v235
	v_cvt_pk_bf16_f32 v235, v36, v37
	v_pk_mul_f32 v[36:37], v[60:61], v[124:125]
	v_cvt_pk_bf16_f32 v236, v236, v237
	v_cvt_pk_bf16_f32 v237, v36, v37
	s_nop 0
	s_nop 0
	s_waitcnt lgkmcnt(8)
	v_mfma_f32_16x16x32_bf16 v[142:145], v[234:237], v[102:105], v[142:145]
	ds_read_b64 v[102:103], v157 offset:448
	ds_read_b64 v[104:105], v157 offset:480
	s_nop 0
	s_nop 0
	s_waitcnt lgkmcnt(8)
	v_mfma_f32_16x16x32_bf16 v[146:149], v[234:237], v[106:109], v[146:149]
	s_nop 0
	s_nop 0
	s_waitcnt lgkmcnt(6)
	v_mfma_f32_16x16x32_bf16 v[238:241], v[234:237], v[110:113], v[150:153]
	s_nop 2
	s_nop 0
	s_nop 0
	s_waitcnt lgkmcnt(4)
	v_mfma_f32_16x16x32_bf16 v[138:141], v[234:237], v[114:117], v[138:141]
	s_nop 0
	s_nop 0
	s_nop 0
	s_waitcnt lgkmcnt(3)
	v_pk_mul_f32 v[36:37], v[64:65], v[128:129]
	v_pk_mul_f32 v[150:151], v[62:63], v[126:127]
	v_cvt_pk_bf16_f32 v243, v36, v37
	v_cvt_pk_bf16_f32 v242, v150, v151
	s_waitcnt lgkmcnt(2)
	v_pk_mul_f32 v[36:37], v[68:69], v[120:121]
	v_pk_mul_f32 v[150:151], v[66:67], v[118:119]
	v_cvt_pk_bf16_f32 v245, v36, v37
	v_cvt_pk_bf16_f32 v244, v150, v151
	s_nop 0
	ds_read_b64 v[106:107], v1 offset:704
	ds_read_b64 v[108:109], v1 offset:736
	ds_read_b64 v[234:235], v246 offset:1216
	ds_read_b64 v[236:237], v246 offset:1248
	s_nop 0
	s_waitcnt lgkmcnt(4)
	v_mfma_f32_16x16x32_bf16 v[150:153], v[242:245], v[102:105], v[142:145]
	s_nop 2
	s_nop 0
	s_nop 0
	s_waitcnt lgkmcnt(2)
	v_mfma_f32_16x16x32_bf16 v[146:149], v[242:245], v[106:109], v[146:149]
	ds_read_b64 v[142:143], v35 offset:960
	ds_read_b64 v[144:145], v35 offset:992
	s_waitcnt lgkmcnt(0)
	s_barrier
	v_mfma_f32_16x16x32_bf16 v[142:145], v[242:245], v[142:145], v[238:241]
	v_mfma_f32_16x16x32_bf16 v[138:141], v[242:245], v[234:237], v[138:141]
	s_cbranch_vccnz .LBB0_719
	v_mov_b32_e32 v1, v158
	s_mov_b32 s22, s79
	v_ashrrev_i32_e32 v35, 5, v1
	v_lshlrev_b32_e32 v1, 4, v1
	v_and_b32_e32 v1, 0x1f0, v1
	v_mul_lo_u32 v35, v35, s84
	v_add3_u32 v1, 0, v1, v35
	s_waitcnt vmcnt(0)
	ds_write_b128 v1, v[70:73]
	ds_write_b128 v1, v[74:77] offset:33792
	ds_write_b128 v1, v[78:81] offset:8448
	ds_write_b128 v1, v[82:85] offset:42240
	ds_write_b128 v1, v[86:89] offset:16896
	ds_write_b128 v1, v[90:93] offset:50688
	ds_write_b128 v1, v[94:97] offset:25344
	ds_write_b128 v1, v[98:101] offset:59136
	v_mov_b32_e32 v1, v158
	s_lshl_b32 s26, s22, 6
	s_add_i32 s22, s22, s75
	s_ashr_i32 s23, s22, 31
	s_ashr_i32 s27, s26, 31
	s_sub_i32 s80, s7, s26
	s_lshl_b64 s[24:25], s[22:23], 17
	s_add_u32 s24, s73, s24
	v_lshlrev_b32_e32 v36, 3, v1
	s_addc_u32 s25, s74, s25
	v_mov_b32_e32 v37, v34
	v_lshl_add_u64 v[110:111], v[36:37], 1, s[24:25]
	s_movk_i32 s24, 0x2000
	v_add_co_u32_e32 v106, vcc, s24, v110
	s_movk_i32 s24, 0x4000
	s_nop 0
	v_addc_co_u32_e32 v107, vcc, 0, v111, vcc
	v_add_co_u32_e32 v112, vcc, s24, v110
	s_movk_i32 s24, 0x6000
	s_nop 0
	v_addc_co_u32_e32 v113, vcc, 0, v111, vcc
	v_add_co_u32_e32 v114, vcc, s24, v110
	global_load_dwordx4 v[102:105], v[110:111], off
	s_nop 0
	global_load_dwordx4 v[106:109], v[106:107], off
	v_addc_co_u32_e32 v115, vcc, 0, v111, vcc
	global_load_dwordx4 v[110:113], v[112:113], off
	s_nop 0
	global_load_dwordx4 v[114:117], v[114:115], off
	v_ashrrev_i32_e32 v35, 4, v1
	v_and_b32_e32 v1, 0x78, v36
	s_add_u32 s24, s26, s71
	v_mov_b32_e32 v126, 0
	v_mov_b32_e32 v127, v34
	v_lshl_or_b32 v36, v35, 11, v1
	s_addc_u32 s25, s27, s72
	s_min_i32 s80, s80, 64
	v_mov_b32_e32 v128, v34
	v_mov_b32_e32 v129, v34
	v_mov_b64_e32 v[118:119], v[126:127]
	v_lshl_add_u64 v[36:37], v[36:37], 1, s[14:15]
	v_cmp_gt_i32_e32 vcc, s80, v35
	v_mov_b64_e32 v[120:121], v[128:129]
	s_and_saveexec_b64 s[26:27], vcc
	s_cbranch_execz .LBB0_714
	s_lshl_b64 s[82:83], s[24:25], 12
	v_lshl_add_u64 v[118:119], v[36:37], 0, s[82:83]
	global_load_dwordx4 v[118:121], v[118:119], off

.LBB0_823:
	s_waitcnt vmcnt(0) lgkmcnt(0)
	v_add_f32_e32 v1, 0, v91
	v_add_f32_e32 v1, v120, v1
	v_add_f32_e32 v1, v121, v1
	v_add_f32_e32 v1, v122, v1
	v_add_f32_e32 v1, v123, v1
	v_add_f32_e32 v1, v124, v1
	v_add_f32_e32 v1, v125, v1
	v_add_f32_e32 v1, v126, v1
	v_add_f32_e32 v1, v128, v1
	v_add_f32_e32 v1, v131, v1
	v_add_f32_e32 v1, v134, v1
	v_add_f32_e32 v1, v144, v1
	v_add_f32_e32 v1, v147, v1
	v_add_f32_e32 v1, v155, v1
	v_add_f32_e32 v1, v175, v1
	v_add_f32_e32 v1, v176, v1
	v_add_u32_e32 v35, s93, v129
	ds_write_b128 v156, v[42:45]
	ds_write_b128 v156, v[46:49] offset:8704
	ds_write_b128 v157, v[50:53] offset:53248
	ds_write_b128 v157, v[54:57] offset:61952
	ds_write_b32 v35, v1
	v_add_u32_e32 v35, 0, v129
	v_add_u32_e32 v1, 0x13800, v35
	s_waitcnt lgkmcnt(0)
	s_barrier
	ds_read2st64_b32 v[36:37], v1 offset1:2
	ds_read2st64_b32 v[58:59], v1 offset0:4 offset1:6
	s_andn2_b64 vcc, exec, s[12:13]
	s_waitcnt lgkmcnt(1)
	v_add_f32_e32 v60, 0, v36
	v_cndmask_b32_e64 v61, 0, v37, s[40:41]
	v_cndmask_b32_e64 v36, 0, v60, s[38:39]
	s_waitcnt lgkmcnt(0)
	v_cndmask_b32_e64 v1, 0, v58, s[42:43]
	v_add_f32_e32 v36, v36, v61
	v_cndmask_b32_e64 v62, 0, v59, s[44:45]
	v_add_f32_e32 v1, v36, v1
	v_add_f32_e32 v61, v1, v62
	v_mov_b32_e32 v90, v37
	v_pk_add_f32 v[36:37], v[60:61], v[90:91]
	s_nop 0
	v_add_f32_e32 v1, v36, v58
	v_add_f32_e32 v59, v1, v59
	v_sub_f32_e32 v1, v59, v36
	v_mul_f32_e32 v1, 0x3fb8aa3b, v1
	v_exp_f32_e32 v58, v1
	v_add_u32_e32 v1, s96, v130
	ds_read_u16 v184, v1
	s_nop 0
	v_sub_f32_e32 v62, v37, v36
	v_mul_f32_e32 v62, 0x3fb8aa3b, v62
	v_exp_f32_e32 v63, v62
	v_sub_f32_e32 v62, v36, v37
	s_waitcnt lgkmcnt(1)
	s_waitcnt lgkmcnt(0)
	v_lshlrev_b32_e32 v61, 16, v184
	v_add_f32_e32 v64, v120, v37
	v_mul_f32_e32 v61, v63, v61
	v_cvt_pk_bf16_f32 v61, v61, s0
	s_mul_i32 s0, s76, 0x110
	v_add_u32_e32 v37, s0, v130
	ds_read_u16 v184, v37
	ds_read_u16 v188, v37 offset:272
	ds_read_u16 v192, v37 offset:544
	ds_read_u16 v196, v37 offset:816
	ds_read_u16 v200, v37 offset:1088
	ds_read_u16 v204, v37 offset:1360
	ds_write_b16 v1, v61
	s_nop 0
	v_sub_f32_e32 v63, v64, v36
	v_mul_f32_e32 v63, 0x3fb8aa3b, v63
	v_mul_f32_e32 v60, 0x3fb8aa3b, v91
	v_exp_f32_e32 v66, v63
	s_nop 0
	s_waitcnt lgkmcnt(6)
	v_lshlrev_b32_e32 v65, 16, v184
	ds_read_u16 v184, v37 offset:1632
	v_mul_f32_e32 v61, 0x3fb8aa3b, v120
	v_sub_f32_e32 v63, v36, v64
	v_exp_f32_e32 v60, v60
	v_mul_f32_e32 v62, 0x3fb8aa3b, v62
	v_exp_f32_e32 v61, v61
	v_mul_f32_e32 v63, 0x3fb8aa3b, v63
	v_exp_f32_e32 v62, v62
	v_exp_f32_e32 v63, v63
	v_pk_add_f32 v[60:61], v[60:61], 1.0 op_sel_hi:[1,0] neg_lo:[1,0] neg_hi:[1,0]
	v_mul_f32_e32 v65, v66, v65
	v_cvt_pk_bf16_f32 v65, v65, s0
	v_pk_mul_f32 v[62:63], v[60:61], v[62:63]
	ds_write_b16 v37, v65
	v_cvt_pk_bf16_f32 v60, v62, s0
	ds_write_b16 v1, v60 offset:17408
	v_cvt_pk_bf16_f32 v1, v63, s0
	ds_write_b16 v37, v1 offset:17408
	v_add_f32_e32 v1, v121, v64
	v_pk_mul_f32 v[60:61], v[58:59], v[62:63] op_sel_hi:[0,1]
	s_nop 0
	v_sub_f32_e32 v64, v1, v36
	v_mul_f32_e32 v64, 0x3fb8aa3b, v64
	v_exp_f32_e32 v65, v64
	v_sub_f32_e32 v64, v36, v1
	s_nop 0
	s_waitcnt lgkmcnt(9)
	v_lshlrev_b32_e32 v63, 16, v188
	ds_read_u16 v188, v37 offset:1904
	v_add_f32_e32 v1, v122, v1
	v_mul_f32_e32 v63, v65, v63
	v_cvt_pk_bf16_f32 v63, v63, s0
	ds_write_b16 v37, v63 offset:272
	s_nop 0
	v_sub_f32_e32 v65, v1, v36
	v_mul_f32_e32 v65, 0x3fb8aa3b, v65
	v_mul_f32_e32 v62, 0x3fb8aa3b, v121
	v_exp_f32_e32 v67, v65
	s_nop 0
	s_waitcnt lgkmcnt(10)
	v_lshlrev_b32_e32 v66, 16, v192
	ds_read_u16 v192, v37 offset:2176
	v_mul_f32_e32 v63, 0x3fb8aa3b, v122
	v_sub_f32_e32 v65, v36, v1
	v_exp_f32_e32 v62, v62
	v_mul_f32_e32 v64, 0x3fb8aa3b, v64
	v_exp_f32_e32 v63, v63
	v_mul_f32_e32 v65, 0x3fb8aa3b, v65
	v_exp_f32_e32 v64, v64
	v_exp_f32_e32 v65, v65
	v_pk_add_f32 v[62:63], v[62:63], 1.0 op_sel_hi:[1,0] neg_lo:[1,0] neg_hi:[1,0]
	v_mul_f32_e32 v66, v67, v66
	v_cvt_pk_bf16_f32 v66, v66, s0
	v_pk_mul_f32 v[64:65], v[62:63], v[64:65]
	v_add_f32_e32 v1, v123, v1
	v_cvt_pk_bf16_f32 v62, v64, s0
	ds_write_b16 v37, v62 offset:17680
	v_pk_mul_f32 v[62:63], v[58:59], v[64:65] op_sel_hi:[0,1]
	v_cvt_pk_bf16_f32 v64, v65, s0
	ds_write_b16 v37, v66 offset:544
	ds_write_b16 v37, v64 offset:17952
	s_nop 0
	v_sub_f32_e32 v66, v1, v36
	v_mul_f32_e32 v66, 0x3fb8aa3b, v66
	v_exp_f32_e32 v67, v66
	v_sub_f32_e32 v66, v36, v1
	s_nop 0
	s_waitcnt lgkmcnt(13)
	v_lshlrev_b32_e32 v65, 16, v196
	ds_read_u16 v196, v37 offset:2448
	v_add_f32_e32 v1, v124, v1
	v_mul_f32_e32 v65, v67, v65
	v_cvt_pk_bf16_f32 v65, v65, s0
	ds_write_b16 v37, v65 offset:816
	s_nop 0
	v_sub_f32_e32 v67, v1, v36
	v_mul_f32_e32 v67, 0x3fb8aa3b, v67
	v_mul_f32_e32 v64, 0x3fb8aa3b, v123
	v_exp_f32_e32 v69, v67
	s_nop 0
	s_waitcnt lgkmcnt(14)
	v_lshlrev_b32_e32 v68, 16, v200
	ds_read_u16 v200, v37 offset:2720
	v_mul_f32_e32 v65, 0x3fb8aa3b, v124
	v_sub_f32_e32 v67, v36, v1
	v_exp_f32_e32 v64, v64
	v_mul_f32_e32 v66, 0x3fb8aa3b, v66
	v_exp_f32_e32 v65, v65
	v_mul_f32_e32 v67, 0x3fb8aa3b, v67
	v_exp_f32_e32 v66, v66
	v_exp_f32_e32 v67, v67
	v_pk_add_f32 v[64:65], v[64:65], 1.0 op_sel_hi:[1,0] neg_lo:[1,0] neg_hi:[1,0]
	v_mul_f32_e32 v68, v69, v68
	v_cvt_pk_bf16_f32 v68, v68, s0
	v_pk_mul_f32 v[66:67], v[64:65], v[66:67]
	v_add_f32_e32 v1, v125, v1
	v_cvt_pk_bf16_f32 v64, v66, s0
	ds_write_b16 v37, v64 offset:18224
	v_pk_mul_f32 v[64:65], v[58:59], v[66:67] op_sel_hi:[0,1]
	v_cvt_pk_bf16_f32 v66, v67, s0
	ds_write_b16 v37, v68 offset:1088
	ds_write_b16 v37, v66 offset:18496
	s_nop 0
	v_sub_f32_e32 v68, v1, v36
	v_mul_f32_e32 v68, 0x3fb8aa3b, v68
	v_exp_f32_e32 v69, v68
	v_sub_f32_e32 v68, v36, v1
	s_nop 0
	s_waitcnt lgkmcnt(15)
	v_lshlrev_b32_e32 v67, 16, v204
	ds_read_u16 v204, v37 offset:2992
	v_add_f32_e32 v1, v126, v1
	v_mul_f32_e32 v67, v69, v67
	v_cvt_pk_bf16_f32 v67, v67, s0
	ds_write_b16 v37, v67 offset:1360
	s_nop 0
	v_sub_f32_e32 v69, v1, v36
	v_mul_f32_e32 v69, 0x3fb8aa3b, v69
	v_mul_f32_e32 v66, 0x3fb8aa3b, v125
	v_exp_f32_e32 v71, v69
	s_nop 0
	s_waitcnt lgkmcnt(15)
	v_lshlrev_b32_e32 v70, 16, v184
	ds_read_u16 v184, v37 offset:3264
	v_mul_f32_e32 v67, 0x3fb8aa3b, v126
	v_sub_f32_e32 v69, v36, v1
	v_exp_f32_e32 v66, v66
	v_mul_f32_e32 v68, 0x3fb8aa3b, v68
	v_exp_f32_e32 v67, v67
	v_mul_f32_e32 v69, 0x3fb8aa3b, v69
	v_exp_f32_e32 v68, v68
	v_exp_f32_e32 v69, v69
	v_pk_add_f32 v[66:67], v[66:67], 1.0 op_sel_hi:[1,0] neg_lo:[1,0] neg_hi:[1,0]
	v_mul_f32_e32 v70, v71, v70
	v_cvt_pk_bf16_f32 v70, v70, s0
	v_pk_mul_f32 v[66:67], v[66:67], v[68:69]
	v_cvt_pk_bf16_f32 v60, v60, v61
	v_cvt_pk_bf16_f32 v68, v66, s0
	ds_write_b16 v37, v68 offset:18768
	v_pk_mul_f32 v[68:69], v[58:59], v[66:67] op_sel_hi:[0,1]
	v_cvt_pk_bf16_f32 v66, v67, s0
	v_cvt_pk_bf16_f32 v61, v62, v63
	v_cvt_pk_bf16_f32 v62, v64, v65
	v_cvt_pk_bf16_f32 v63, v68, v69
	ds_write_b16 v37, v70 offset:1632
	ds_write_b16 v37, v66 offset:19040
	ds_write_b128 v158, v[60:63] offset:34816
	v_add_f32_e32 v1, v128, v1
	s_nop 0
	v_sub_f32_e32 v62, v1, v36
	v_mul_f32_e32 v62, 0x3fb8aa3b, v62
	v_exp_f32_e32 v63, v62
	v_sub_f32_e32 v62, v36, v1
	s_nop 0
	s_waitcnt lgkmcnt(15)
	v_lshlrev_b32_e32 v61, 16, v188
	ds_read_u16 v188, v37 offset:3536
	v_add_f32_e32 v1, v131, v1
	v_mul_f32_e32 v61, v63, v61
	v_cvt_pk_bf16_f32 v61, v61, s0
	ds_write_b16 v37, v61 offset:1904
	s_nop 0
	v_sub_f32_e32 v63, v1, v36
	v_mul_f32_e32 v63, 0x3fb8aa3b, v63
	v_mul_f32_e32 v60, 0x3fb8aa3b, v128
	v_exp_f32_e32 v65, v63
	s_nop 0
	s_waitcnt lgkmcnt(15)
	v_lshlrev_b32_e32 v64, 16, v192
	ds_read_u16 v192, v37 offset:3808
	v_mul_f32_e32 v61, 0x3fb8aa3b, v131
	v_sub_f32_e32 v63, v36, v1
	v_exp_f32_e32 v60, v60
	v_mul_f32_e32 v62, 0x3fb8aa3b, v62
	v_exp_f32_e32 v61, v61
	v_mul_f32_e32 v63, 0x3fb8aa3b, v63
	v_exp_f32_e32 v62, v62
	v_exp_f32_e32 v63, v63
	v_pk_add_f32 v[60:61], v[60:61], 1.0 op_sel_hi:[1,0] neg_lo:[1,0] neg_hi:[1,0]
	v_mul_f32_e32 v64, v65, v64
	v_cvt_pk_bf16_f32 v64, v64, s0
	v_pk_mul_f32 v[62:63], v[60:61], v[62:63]
	v_add_f32_e32 v1, v134, v1
	v_cvt_pk_bf16_f32 v60, v62, s0
	ds_write_b16 v37, v60 offset:19312
	v_pk_mul_f32 v[60:61], v[58:59], v[62:63] op_sel_hi:[0,1]
	v_cvt_pk_bf16_f32 v62, v63, s0
	ds_write_b16 v37, v64 offset:2176
	ds_write_b16 v37, v62 offset:19584
	s_nop 0
	v_sub_f32_e32 v64, v1, v36
	v_mul_f32_e32 v64, 0x3fb8aa3b, v64
	v_exp_f32_e32 v65, v64
	v_sub_f32_e32 v64, v36, v1
	s_nop 0
	s_waitcnt lgkmcnt(15)
	v_lshlrev_b32_e32 v63, 16, v196
	v_add_f32_e32 v1, v144, v1
	v_mul_f32_e32 v63, v65, v63
	v_cvt_pk_bf16_f32 v63, v63, s0
	ds_write_b16 v37, v63 offset:2448
	s_nop 0
	v_sub_f32_e32 v65, v1, v36
	v_mul_f32_e32 v65, 0x3fb8aa3b, v65
	v_mul_f32_e32 v62, 0x3fb8aa3b, v134
	v_exp_f32_e32 v67, v65
	s_nop 0
	s_waitcnt lgkmcnt(15)
	v_lshlrev_b32_e32 v66, 16, v200
	v_mul_f32_e32 v63, 0x3fb8aa3b, v144
	v_sub_f32_e32 v65, v36, v1
	v_exp_f32_e32 v62, v62
	v_mul_f32_e32 v64, 0x3fb8aa3b, v64
	v_exp_f32_e32 v63, v63
	v_mul_f32_e32 v65, 0x3fb8aa3b, v65
	v_exp_f32_e32 v64, v64
	v_exp_f32_e32 v65, v65
	v_pk_add_f32 v[62:63], v[62:63], 1.0 op_sel_hi:[1,0] neg_lo:[1,0] neg_hi:[1,0]
	v_mul_f32_e32 v66, v67, v66
	v_cvt_pk_bf16_f32 v66, v66, s0
	v_pk_mul_f32 v[64:65], v[62:63], v[64:65]
	v_add_f32_e32 v1, v147, v1
	v_cvt_pk_bf16_f32 v62, v64, s0
	ds_write_b16 v37, v62 offset:19856
	v_pk_mul_f32 v[62:63], v[58:59], v[64:65] op_sel_hi:[0,1]
	v_cvt_pk_bf16_f32 v64, v65, s0
	ds_write_b16 v37, v66 offset:2720
	ds_write_b16 v37, v64 offset:20128
	s_nop 0
	v_sub_f32_e32 v66, v1, v36
	v_mul_f32_e32 v66, 0x3fb8aa3b, v66
	v_exp_f32_e32 v67, v66
	v_sub_f32_e32 v66, v36, v1
	s_nop 0
	s_waitcnt lgkmcnt(15)
	v_lshlrev_b32_e32 v65, 16, v204
	v_add_f32_e32 v1, v155, v1
	v_mul_f32_e32 v65, v67, v65
	v_cvt_pk_bf16_f32 v65, v65, s0
	ds_write_b16 v37, v65 offset:2992
	s_nop 0
	v_sub_f32_e32 v67, v1, v36
	v_mul_f32_e32 v67, 0x3fb8aa3b, v67
	v_mul_f32_e32 v64, 0x3fb8aa3b, v147
	v_exp_f32_e32 v69, v67
	s_nop 0
	s_waitcnt lgkmcnt(15)
	v_lshlrev_b32_e32 v68, 16, v184
	v_mul_f32_e32 v65, 0x3fb8aa3b, v155
	v_sub_f32_e32 v67, v36, v1
	v_exp_f32_e32 v64, v64
	v_mul_f32_e32 v66, 0x3fb8aa3b, v66
	v_exp_f32_e32 v65, v65
	v_mul_f32_e32 v67, 0x3fb8aa3b, v67
	v_exp_f32_e32 v66, v66
	v_exp_f32_e32 v67, v67
	v_pk_add_f32 v[64:65], v[64:65], 1.0 op_sel_hi:[1,0] neg_lo:[1,0] neg_hi:[1,0]
	v_mul_f32_e32 v68, v69, v68
	v_cvt_pk_bf16_f32 v68, v68, s0
	v_pk_mul_f32 v[66:67], v[64:65], v[66:67]
	v_add_f32_e32 v1, v175, v1
	v_cvt_pk_bf16_f32 v64, v66, s0
	ds_write_b16 v37, v64 offset:20400
	v_pk_mul_f32 v[64:65], v[58:59], v[66:67] op_sel_hi:[0,1]
	v_cvt_pk_bf16_f32 v66, v67, s0
	ds_write_b16 v37, v68 offset:3264
	ds_write_b16 v37, v66 offset:20672
	s_nop 0
	v_sub_f32_e32 v68, v1, v36
	v_mul_f32_e32 v68, 0x3fb8aa3b, v68
	v_exp_f32_e32 v69, v68
	v_sub_f32_e32 v68, v36, v1
	s_nop 0
	s_waitcnt lgkmcnt(13)
	v_lshlrev_b32_e32 v67, 16, v188
	v_add_f32_e32 v1, v176, v1
	v_mul_f32_e32 v67, v69, v67
	v_cvt_pk_bf16_f32 v67, v67, s0
	ds_write_b16 v37, v67 offset:3536
	s_nop 0
	v_sub_f32_e32 v69, v1, v36
	v_mul_f32_e32 v66, 0x3fb8aa3b, v175
	v_mul_f32_e32 v69, 0x3fb8aa3b, v69
	v_sub_f32_e32 v1, v36, v1
	s_nop 0
	s_waitcnt lgkmcnt(12)
	v_lshlrev_b32_e32 v70, 16, v192
	v_mul_f32_e32 v67, 0x3fb8aa3b, v176
	v_exp_f32_e32 v66, v66
	v_mul_f32_e32 v68, 0x3fb8aa3b, v68
	v_exp_f32_e32 v67, v67
	v_exp_f32_e32 v71, v69
	v_mul_f32_e32 v1, 0x3fb8aa3b, v1
	v_exp_f32_e32 v68, v68
	v_exp_f32_e32 v69, v1
	v_mul_f32_e32 v1, v71, v70
	v_pk_add_f32 v[66:67], v[66:67], 1.0 op_sel_hi:[1,0] neg_lo:[1,0] neg_hi:[1,0]
	v_cvt_pk_bf16_f32 v1, v1, s0
	v_pk_mul_f32 v[66:67], v[66:67], v[68:69]
	ds_write_b16 v37, v1 offset:3808
	v_cvt_pk_bf16_f32 v1, v66, s0
	v_pk_mul_f32 v[68:69], v[58:59], v[66:67] op_sel_hi:[0,1]
	ds_write_b16 v37, v1 offset:20944
	v_cvt_pk_bf16_f32 v1, v67, s0
	v_cvt_pk_bf16_f32 v60, v60, v61
	v_cvt_pk_bf16_f32 v61, v62, v63
	v_cvt_pk_bf16_f32 v62, v64, v65
	v_cvt_pk_bf16_f32 v63, v68, v69
	ds_write_b16 v37, v1 offset:21216
	ds_write_b128 v158, v[60:63] offset:34832
	s_cbranch_vccnz .LBB0_825
	v_mul_f32_e32 v1, 0x3fb8aa3b, v36
	v_exp_f32_e32 v1, v1
	v_mul_f32_e32 v36, 0x3fb8aa3b, v59
	v_exp_f32_e32 v36, v36
	v_add_u32_e32 v37, 0x14000, v35
	ds_write_b32 v37, v1
	v_add_u32_e32 v1, 0x14200, v35
	ds_write_b32 v1, v36

.LBB0_839:
	s_nop 7
	v_cndmask_b32_e64 v1, v66, 0, s[54:55]
	v_cndmask_b32_e64 v35, v67, 0, s[56:57]
	v_cndmask_b32_e64 v37, v68, 0, s[58:59]
	v_cndmask_b32_e64 v67, v69, 0, s[60:61]
	v_cvt_pk_bf16_f32 v66, v1, v35
	v_cvt_pk_bf16_f32 v67, v37, v67
	ds_write_b64 v161, v[66:67]
	ds_read_b128 v[184:187], v132
	ds_read_b128 v[188:191], v135
	s_nop 0
	s_nop 0
	v_add_u32_e32 v1, 0x1000, v162
	ds_read_b64 v[192:193], v1 offset:256
	ds_read_b64 v[194:195], v1 offset:288
	ds_read_b64 v[196:197], v162
	ds_read_b64 v[198:199], v162 offset:32
	v_add_u32_e32 v35, 0x2000, v162
	ds_read_b64 v[200:201], v35 offset:512
	ds_read_b64 v[202:203], v35 offset:544
	v_add_u32_e32 v37, 0x3000, v162
	ds_read_b64 v[204:205], v37 offset:768
	ds_read_b64 v[206:207], v37 offset:800
	s_waitcnt lgkmcnt(11)
	s_waitcnt lgkmcnt(9)
	v_pk_mul_f32 v[68:69], v[4:5], v[186:187]
	ds_read_b128 v[208:211], v136
	v_pk_mul_f32 v[66:67], v[2:3], v[184:185]
	s_waitcnt lgkmcnt(9)
	v_pk_mul_f32 v[72:73], v[12:13], v[190:191]
	ds_read_b128 v[184:187], v137
	v_cvt_pk_bf16_f32 v66, v66, v67
	v_cvt_pk_bf16_f32 v67, v68, v69
	v_pk_mul_f32 v[68:69], v[10:11], v[188:189]
	s_nop 0
	v_cvt_pk_bf16_f32 v68, v68, v69
	v_cvt_pk_bf16_f32 v69, v72, v73
	s_nop 0
	s_nop 0
	s_nop 0
	s_nop 0
	s_waitcnt lgkmcnt(6)
	v_mfma_f32_16x16x32_bf16 v[70:73], v[66:69], v[196:199], 0
	s_sub_i32 s5, s8, 64
	s_add_u32 s18, s5, s72
	s_addc_u32 s19, 0, s74
	v_mfma_f32_16x16x32_bf16 v[74:77], v[66:69], v[192:195], 0
	ds_read_b64 v[188:189], v162 offset:64
	ds_read_b64 v[190:191], v162 offset:96
	ds_read_b64 v[192:193], v1 offset:320
	ds_read_b64 v[194:195], v1 offset:352
	v_mov_b32_e32 v36, 0
	v_cmp_gt_i32_e64 s[68:69], s9, v95
	v_or_b32_e32 v116, s18, v95
	s_waitcnt lgkmcnt(8)
	v_mfma_f32_16x16x32_bf16 v[78:81], v[66:69], v[200:203], 0
	ds_read_b64 v[196:197], v35 offset:576
	ds_read_b64 v[198:199], v35 offset:608
	s_waitcnt lgkmcnt(8)
	v_mfma_f32_16x16x32_bf16 v[66:69], v[66:69], v[204:207], 0
	ds_read_b64 v[200:201], v37 offset:832
	ds_read_b64 v[202:203], v37 offset:864
	s_nop 0
	s_nop 0
	s_nop 0
	s_waitcnt lgkmcnt(9)
	v_pk_mul_f32 v[106:107], v[8:9], v[210:211]
	ds_read_b128 v[204:207], v138
	v_pk_mul_f32 v[104:105], v[6:7], v[208:209]
	s_waitcnt lgkmcnt(9)
	v_pk_mul_f32 v[110:111], v[16:17], v[186:187]
	ds_read_b128 v[208:211], v139
	v_cvt_pk_bf16_f32 v104, v104, v105
	v_cvt_pk_bf16_f32 v105, v106, v107
	v_pk_mul_f32 v[106:107], v[14:15], v[184:185]
	s_nop 0
	v_cvt_pk_bf16_f32 v106, v106, v107
	v_cvt_pk_bf16_f32 v107, v110, v111
	s_nop 0
	s_nop 0
	s_waitcnt lgkmcnt(8)
	v_mfma_f32_16x16x32_bf16 v[70:73], v[104:107], v[188:191], v[70:73]
	ds_read_b64 v[184:185], v162 offset:128
	ds_read_b64 v[186:187], v162 offset:160
	s_nop 0
	s_nop 0
	s_waitcnt lgkmcnt(8)
	v_mfma_f32_16x16x32_bf16 v[74:77], v[104:107], v[192:195], v[74:77]
	ds_read_b64 v[188:189], v1 offset:384
	ds_read_b64 v[190:191], v1 offset:416
	s_nop 0
	s_nop 0
	s_waitcnt lgkmcnt(8)
	v_mfma_f32_16x16x32_bf16 v[78:81], v[104:107], v[196:199], v[78:81]
	ds_read_b64 v[192:193], v35 offset:640
	ds_read_b64 v[194:195], v35 offset:672
	s_nop 0
	s_nop 0
	s_waitcnt lgkmcnt(8)
	v_mfma_f32_16x16x32_bf16 v[66:69], v[104:107], v[200:203], v[66:69]
	ds_read_b64 v[196:197], v37 offset:896
	ds_read_b64 v[198:199], v37 offset:928
	s_nop 0
	s_nop 0
	s_nop 0
	s_waitcnt lgkmcnt(9)
	v_pk_mul_f32 v[106:107], v[20:21], v[206:207]
	ds_read_b128 v[200:203], v140
	v_pk_mul_f32 v[104:105], v[18:19], v[204:205]
	s_waitcnt lgkmcnt(9)
	v_pk_mul_f32 v[110:111], v[24:25], v[210:211]
	ds_read_b128 v[204:207], v141
	v_cvt_pk_bf16_f32 v104, v104, v105
	v_cvt_pk_bf16_f32 v105, v106, v107
	v_pk_mul_f32 v[106:107], v[22:23], v[208:209]
	s_nop 0
	v_cvt_pk_bf16_f32 v106, v106, v107
	v_cvt_pk_bf16_f32 v107, v110, v111
	s_nop 0
	s_nop 0
	s_waitcnt lgkmcnt(8)
	v_mfma_f32_16x16x32_bf16 v[70:73], v[104:107], v[184:187], v[70:73]
	ds_read_b64 v[184:185], v162 offset:192
	ds_read_b64 v[186:187], v162 offset:224
	s_nop 0
	s_nop 0
	s_waitcnt lgkmcnt(8)
	v_mfma_f32_16x16x32_bf16 v[74:77], v[104:107], v[188:191], v[74:77]
	ds_read_b64 v[188:189], v1 offset:448
	ds_read_b64 v[190:191], v1 offset:480
	s_nop 0
	s_nop 0
	s_waitcnt lgkmcnt(8)
	v_mfma_f32_16x16x32_bf16 v[78:81], v[104:107], v[192:195], v[78:81]
	ds_read_b64 v[192:193], v35 offset:704
	ds_read_b64 v[194:195], v35 offset:736
	s_nop 0
	s_nop 0
	s_waitcnt lgkmcnt(8)
	v_mfma_f32_16x16x32_bf16 v[66:69], v[104:107], v[196:199], v[66:69]
	s_nop 0
	s_nop 0
	s_nop 0
	s_waitcnt lgkmcnt(7)
	v_pk_mul_f32 v[106:107], v[28:29], v[202:203]
	v_pk_mul_f32 v[104:105], v[26:27], v[200:201]
	s_waitcnt lgkmcnt(6)
	v_pk_mul_f32 v[110:111], v[32:33], v[206:207]
	v_cvt_pk_bf16_f32 v104, v104, v105
	v_cvt_pk_bf16_f32 v105, v106, v107
	v_pk_mul_f32 v[106:107], v[30:31], v[204:205]
	s_nop 0
	v_cvt_pk_bf16_f32 v106, v106, v107
	v_cvt_pk_bf16_f32 v107, v110, v111
	s_nop 0
	s_nop 0
	s_waitcnt lgkmcnt(4)
	v_mfma_f32_16x16x32_bf16 v[108:111], v[104:107], v[184:187], v[70:73]
	s_nop 2
	s_nop 0
	s_nop 0
	s_waitcnt lgkmcnt(2)
	v_mfma_f32_16x16x32_bf16 v[74:77], v[104:107], v[188:191], v[74:77]
	s_nop 0
	s_nop 0
	s_waitcnt lgkmcnt(0)
	v_mfma_f32_16x16x32_bf16 v[70:73], v[104:107], v[192:195], v[78:81]
	s_nop 2
	ds_read_b64 v[78:79], v37 offset:960
	ds_read_b64 v[80:81], v37 offset:992
	s_nop 0
	s_waitcnt lgkmcnt(0)
	v_mfma_f32_16x16x32_bf16 v[66:69], v[104:107], v[78:81], v[66:69]
	s_barrier
	ds_read_b128 v[78:81], v174
	ds_read_b128 v[104:107], v174 offset:64
	s_waitcnt lgkmcnt(0)
	v_mfma_f32_16x16x32_bf16 v[78:81], v[62:65], v[78:81], v[108:111]
	v_mov_b32_e32 v37, 0
	v_mfma_f32_16x16x32_bf16 v[78:81], v[58:61], v[104:107], v[78:81]
	s_and_saveexec_b64 s[20:21], s[68:69]
	s_cbranch_execz .LBB0_841
	v_mov_b32_e32 v117, s19
	v_lshlrev_b64 v[36:37], 12, v[116:117]
	v_lshl_add_u64 v[36:37], v[102:103], 0, v[36:37]
	global_load_dwordx2 v[36:37], v[36:37], off

.LBB0_969:
	s_add_i32 s20, s25, -3
	s_cmp_ge_u32 s20, s15
	v_mov_b32_e32 v45, 0
	s_cbranch_scc1 .LBB0_971
	s_add_i32 s20, s20, s22
	s_ashr_i32 s21, s20, 31
	s_lshl_b64 s[20:21], s[20:21], 13
	v_lshl_add_u64 v[38:39], v[46:47], 0, s[20:21]
	global_load_dword v45, v[38:39], off

.LBB0_975:
	s_add_i32 s18, s25, -2
	s_cmp_ge_u32 s18, s15
	v_mov_b32_e32 v60, 0
	s_cbranch_scc1 .LBB0_977
	s_add_i32 s18, s18, s22
	s_ashr_i32 s19, s18, 31
	s_lshl_b64 s[18:19], s[18:19], 13
	v_lshl_add_u64 v[38:39], v[46:47], 0, s[18:19]
	global_load_dword v60, v[38:39], off

.LBB0_981:
	s_cmp_gt_u32 s25, s15
	v_mov_b32_e32 v61, 0
	s_cbranch_scc1 .LBB0_983
	s_add_i32 s18, s22, s25
	s_add_i32 s18, s18, -1
	s_ashr_i32 s19, s18, 31
	s_lshl_b64 s[18:19], s[18:19], 13
	v_lshl_add_u64 v[38:39], v[46:47], 0, s[18:19]
	global_load_dword v61, v[38:39], off

.LBB0_987:
	s_cmp_ge_u32 s25, s15
	v_mov_b32_e32 v62, 0
	s_cbranch_scc1 .LBB0_989
	s_add_i32 s18, s25, s22
	s_ashr_i32 s19, s18, 31
	s_lshl_b64 s[18:19], s[18:19], 13
	v_lshl_add_u64 v[38:39], v[46:47], 0, s[18:19]
	global_load_dword v62, v[38:39], off

.LBB0_993:
	s_add_i32 s18, s25, 1
	s_cmp_ge_u32 s18, s15
	v_mov_b32_e32 v63, 0
	s_cbranch_scc1 .LBB0_995
	s_add_i32 s18, s18, s22
	s_ashr_i32 s19, s18, 31
	s_lshl_b64 s[18:19], s[18:19], 13
	v_lshl_add_u64 v[38:39], v[46:47], 0, s[18:19]
	global_load_dword v63, v[38:39], off

.LBB0_999:
	s_add_i32 s18, s25, 2
	s_cmp_ge_u32 s18, s15
	v_mov_b32_e32 v64, 0
	s_cbranch_scc1 .LBB0_1001
	s_add_i32 s18, s18, s22
	s_ashr_i32 s19, s18, 31
	s_lshl_b64 s[18:19], s[18:19], 13
	v_lshl_add_u64 v[38:39], v[46:47], 0, s[18:19]
	global_load_dword v64, v[38:39], off

.LBB0_1005:
	s_add_i32 s18, s25, 3
	s_cmp_ge_u32 s18, s15
	v_mov_b32_e32 v65, 0
	s_cbranch_scc1 .LBB0_1007
	s_add_i32 s18, s18, s22
	s_ashr_i32 s19, s18, 31
	s_lshl_b64 s[18:19], s[18:19], 13
	v_lshl_add_u64 v[38:39], v[46:47], 0, s[18:19]
	global_load_dword v65, v[38:39], off

.LBB0_1011:
	s_add_i32 s18, s25, 4
	s_cmp_ge_u32 s18, s15
	v_mov_b32_e32 v66, 0
	s_cbranch_scc1 .LBB0_1013
	s_add_i32 s18, s18, s22
	s_ashr_i32 s19, s18, 31
	s_lshl_b64 s[18:19], s[18:19], 13
	v_lshl_add_u64 v[38:39], v[46:47], 0, s[18:19]
	global_load_dword v66, v[38:39], off

.LBB0_1017:
	s_add_i32 s18, s25, 5
	s_cmp_ge_u32 s18, s15
	v_mov_b32_e32 v67, 0
	s_cbranch_scc1 .LBB0_1019
	s_add_i32 s18, s18, s22
	s_ashr_i32 s19, s18, 31
	s_lshl_b64 s[18:19], s[18:19], 13
	v_lshl_add_u64 v[38:39], v[46:47], 0, s[18:19]
	global_load_dword v67, v[38:39], off

.LBB0_1023:
	s_add_i32 s18, s25, 6
	s_cmp_ge_u32 s18, s15
	v_mov_b32_e32 v68, 0
	s_cbranch_scc1 .LBB0_1025
	s_add_i32 s18, s18, s22
	s_ashr_i32 s19, s18, 31
	s_lshl_b64 s[18:19], s[18:19], 13
	v_lshl_add_u64 v[38:39], v[46:47], 0, s[18:19]
	global_load_dword v68, v[38:39], off

.LBB0_1029:
	s_add_i32 s18, s25, 7
	s_cmp_ge_u32 s18, s15
	v_mov_b32_e32 v69, 0
	s_cbranch_scc1 .LBB0_1031
	s_add_i32 s18, s18, s22
	s_ashr_i32 s19, s18, 31
	s_lshl_b64 s[18:19], s[18:19], 13
	v_lshl_add_u64 v[38:39], v[46:47], 0, s[18:19]
	global_load_dword v69, v[38:39], off

.LBB0_1035:
	s_add_i32 s18, s25, 8
	s_cmp_ge_u32 s18, s15
	v_mov_b32_e32 v70, 0
	s_cbranch_scc1 .LBB0_1037
	s_add_i32 s18, s18, s22
	s_ashr_i32 s19, s18, 31
	s_lshl_b64 s[18:19], s[18:19], 13
	v_lshl_add_u64 v[38:39], v[46:47], 0, s[18:19]
	global_load_dword v70, v[38:39], off

.LBB0_1041:
	s_add_i32 s18, s25, 9
	s_cmp_ge_u32 s18, s15
	v_mov_b32_e32 v82, 0
	s_cbranch_scc1 .LBB0_1043
	s_add_i32 s18, s18, s22
	s_ashr_i32 s19, s18, 31
	s_lshl_b64 s[18:19], s[18:19], 13
	v_lshl_add_u64 v[38:39], v[46:47], 0, s[18:19]
	global_load_dword v82, v[38:39], off

.LBB0_1047:
	s_add_i32 s18, s25, 10
	s_cmp_ge_u32 s18, s15
	v_mov_b32_e32 v88, 0
	s_cbranch_scc1 .LBB0_1049
	s_add_i32 s18, s18, s22
	s_ashr_i32 s19, s18, 31
	s_lshl_b64 s[18:19], s[18:19], 13
	v_lshl_add_u64 v[38:39], v[46:47], 0, s[18:19]
	global_load_dword v88, v[38:39], off

.LBB0_1053:
	s_add_i32 s18, s25, 11
	s_cmp_ge_u32 s18, s15
	v_mov_b32_e32 v98, 0
	s_cbranch_scc1 .LBB0_1055
	s_add_i32 s18, s18, s22
	s_ashr_i32 s19, s18, 31
	s_lshl_b64 s[18:19], s[18:19], 13
	v_lshl_add_u64 v[38:39], v[46:47], 0, s[18:19]
	global_load_dword v98, v[38:39], off

.LBB0_1059:
	s_add_i32 s18, s25, 12
	s_cmp_ge_u32 s18, s15
	v_mov_b32_e32 v145, 0
	s_cbranch_scc1 .LBB0_1061
	s_add_i32 s18, s18, s22
	s_ashr_i32 s19, s18, 31
	s_lshl_b64 s[18:19], s[18:19], 13
	v_lshl_add_u64 v[38:39], v[46:47], 0, s[18:19]
	global_load_dword v145, v[38:39], off

.LBB0_1065:
	s_add_i32 s18, s25, 13
	s_cmp_ge_u32 s18, s15
	v_mov_b32_e32 v146, 0
	s_cbranch_scc1 .LBB0_1067
	s_add_i32 s18, s18, s22
	s_ashr_i32 s19, s18, 31
	s_lshl_b64 s[18:19], s[18:19], 13
	v_lshl_add_u64 v[38:39], v[46:47], 0, s[18:19]
	global_load_dword v146, v[38:39], off

.LBB0_1071:
	s_add_i32 s18, s25, 14
	s_cmp_ge_u32 s18, s15
	v_mov_b32_e32 v147, 0
	s_cbranch_scc1 .LBB0_1073
	s_add_i32 s18, s18, s22
	s_ashr_i32 s19, s18, 31
	s_lshl_b64 s[18:19], s[18:19], 13
	v_lshl_add_u64 v[38:39], v[46:47], 0, s[18:19]
	global_load_dword v147, v[38:39], off

.LBB0_1077:
	s_add_i32 s18, s25, 15
	s_cmp_ge_u32 s18, s15
	v_mov_b32_e32 v148, 0
	s_cbranch_scc1 .LBB0_1079
	s_add_i32 s18, s18, s22
	s_ashr_i32 s19, s18, 31
	s_lshl_b64 s[18:19], s[18:19], 13
	v_lshl_add_u64 v[38:39], v[46:47], 0, s[18:19]
	global_load_dword v148, v[38:39], off

.LBB0_1083:
	s_sub_i32 s18, s15, s24
	s_lshl_b64 s[6:7], s[6:7], 1
	s_add_u32 s20, s45, s6
	s_addc_u32 s21, s46, s7
	s_min_i32 s43, s18, 64
	s_ashr_i32 s18, s22, 31
	s_ashr_i32 s19, s24, 31
	s_add_u32 s63, s24, s22
	s_addc_u32 s64, s19, s18
	v_lshlrev_b32_e32 v38, 1, v35
	v_mov_b32_e32 v39, v34
	v_lshl_add_u64 v[48:49], s[20:21], 0, v[38:39]
	v_mov_b32_e32 v84, 0
	s_cmp_ge_i32 s23, s43
	v_mov_b32_e32 v87, 0
	s_cbranch_scc1 .LBB0_1085
	s_ashr_i32 s19, s23, 31
	s_add_u32 s20, s63, s23
	s_addc_u32 s21, s64, s19
	s_lshl_b64 s[20:21], s[20:21], 12
	v_lshl_add_u64 v[72:73], v[48:49], 0, s[20:21]
	global_load_ushort v87, v[72:73], off
.LBB0_1085:
	s_or_b32 s19, s23, 1
	s_cmp_ge_i32 s19, s43
	s_cbranch_scc1 .LBB0_1087
	s_ashr_i32 s21, s19, 31
	s_add_u32 s20, s63, s19
	s_addc_u32 s21, s64, s21
	s_lshl_b64 s[20:21], s[20:21], 12
	v_lshl_add_u64 v[72:73], v[48:49], 0, s[20:21]
	global_load_ushort v84, v[72:73], off
.LBB0_1087:
	s_or_b32 s20, s23, 2
	v_mov_b32_e32 v81, 0
	s_cmp_ge_i32 s20, s43
	v_mov_b32_e32 v86, 0
	s_cbranch_scc1 .LBB0_1089
	s_ashr_i32 s21, s20, 31
	s_add_u32 s24, s63, s20
	s_addc_u32 s25, s64, s21
	s_lshl_b64 s[24:25], s[24:25], 12
	v_lshl_add_u64 v[72:73], v[48:49], 0, s[24:25]
	global_load_ushort v86, v[72:73], off
.LBB0_1089:
	s_or_b32 s21, s23, 3
	s_cmp_ge_i32 s21, s43
	s_cbranch_scc1 .LBB0_1091
	s_ashr_i32 s25, s21, 31
	s_add_u32 s24, s63, s21
	s_addc_u32 s25, s64, s25
	s_lshl_b64 s[24:25], s[24:25], 12
	v_lshl_add_u64 v[72:73], v[48:49], 0, s[24:25]
	global_load_ushort v81, v[72:73], off
.LBB0_1091:
	s_or_b32 s24, s23, 4
	v_mov_b32_e32 v79, 0
	s_cmp_ge_i32 s24, s43
	v_mov_b32_e32 v85, 0
	s_cbranch_scc1 .LBB0_1093
	s_ashr_i32 s25, s24, 31
	s_add_u32 s26, s63, s24
	s_addc_u32 s27, s64, s25
	s_lshl_b64 s[26:27], s[26:27], 12
	v_lshl_add_u64 v[72:73], v[48:49], 0, s[26:27]
	global_load_ushort v85, v[72:73], off
.LBB0_1093:
	s_or_b32 s25, s23, 5
	s_cmp_ge_i32 s25, s43
	s_cbranch_scc1 .LBB0_1095
	s_ashr_i32 s27, s25, 31
	s_add_u32 s26, s63, s25
	s_addc_u32 s27, s64, s27
	s_lshl_b64 s[26:27], s[26:27], 12
	v_lshl_add_u64 v[72:73], v[48:49], 0, s[26:27]
	global_load_ushort v79, v[72:73], off
.LBB0_1095:
	s_or_b32 s26, s23, 6
	v_mov_b32_e32 v77, 0
	s_cmp_ge_i32 s26, s43
	v_mov_b32_e32 v83, 0
	s_cbranch_scc1 .LBB0_1097
	s_ashr_i32 s27, s26, 31
	s_add_u32 s28, s63, s26
	s_addc_u32 s29, s64, s27
	s_lshl_b64 s[28:29], s[28:29], 12
	v_lshl_add_u64 v[72:73], v[48:49], 0, s[28:29]
	global_load_ushort v83, v[72:73], off
.LBB0_1097:
	s_or_b32 s27, s23, 7
	s_cmp_ge_i32 s27, s43
	s_cbranch_scc1 .LBB0_1099
	s_ashr_i32 s29, s27, 31
	s_add_u32 s28, s63, s27
	s_addc_u32 s29, s64, s29
	s_lshl_b64 s[28:29], s[28:29], 12
	v_lshl_add_u64 v[72:73], v[48:49], 0, s[28:29]
	global_load_ushort v77, v[72:73], off
.LBB0_1099:
	s_or_b32 s28, s23, 8
	v_mov_b32_e32 v75, 0
	s_cmp_ge_i32 s28, s43
	v_mov_b32_e32 v80, 0
	s_cbranch_scc1 .LBB0_1101
	s_ashr_i32 s29, s28, 31
	s_add_u32 s30, s63, s28
	s_addc_u32 s31, s64, s29
	s_lshl_b64 s[30:31], s[30:31], 12
	v_lshl_add_u64 v[72:73], v[48:49], 0, s[30:31]
	global_load_ushort v80, v[72:73], off
.LBB0_1101:
	s_or_b32 s29, s23, 9
	s_cmp_ge_i32 s29, s43
	s_cbranch_scc1 .LBB0_1103
	s_ashr_i32 s31, s29, 31
	s_add_u32 s30, s63, s29
	s_addc_u32 s31, s64, s31
	s_lshl_b64 s[30:31], s[30:31], 12
	v_lshl_add_u64 v[72:73], v[48:49], 0, s[30:31]
	global_load_ushort v75, v[72:73], off
.LBB0_1103:
	s_or_b32 s30, s23, 10
	v_mov_b32_e32 v73, 0
	s_cmp_ge_i32 s30, s43
	v_mov_b32_e32 v78, 0
	s_cbranch_scc1 .LBB0_1105
	s_ashr_i32 s31, s30, 31
	s_add_u32 s34, s63, s30
	s_addc_u32 s35, s64, s31
	s_lshl_b64 s[34:35], s[34:35], 12
	v_lshl_add_u64 v[120:121], v[48:49], 0, s[34:35]
	global_load_ushort v78, v[120:121], off
.LBB0_1105:
	s_or_b32 s31, s23, 11
	s_cmp_ge_i32 s31, s43
	s_cbranch_scc1 .LBB0_1107
	s_ashr_i32 s35, s31, 31
	s_add_u32 s34, s63, s31
	s_addc_u32 s35, s64, s35
	s_lshl_b64 s[34:35], s[34:35], 12
	v_lshl_add_u64 v[72:73], v[48:49], 0, s[34:35]
	global_load_ushort v73, v[72:73], off
.LBB0_1107:
	s_or_b32 s34, s23, 12
	v_mov_b32_e32 v72, 0
	s_cmp_ge_i32 s34, s43
	v_mov_b32_e32 v76, 0
	s_cbranch_scc1 .LBB0_1109
	s_ashr_i32 s35, s34, 31
	s_add_u32 s60, s63, s34
	s_addc_u32 s61, s64, s35
	s_lshl_b64 s[60:61], s[60:61], 12
	v_lshl_add_u64 v[120:121], v[48:49], 0, s[60:61]
	global_load_ushort v76, v[120:121], off
.LBB0_1109:
	s_or_b32 s35, s23, 13
	s_cmp_ge_i32 s35, s43
	s_cbranch_scc1 .LBB0_1111
	s_ashr_i32 s61, s35, 31
	s_add_u32 s60, s63, s35
	s_addc_u32 s61, s64, s61
	s_lshl_b64 s[60:61], s[60:61], 12
	v_lshl_add_u64 v[120:121], v[48:49], 0, s[60:61]
	global_load_ushort v72, v[120:121], off
.LBB0_1111:
	s_or_b32 s60, s23, 14
	v_mov_b32_e32 v71, 0
	s_cmp_ge_i32 s60, s43
	v_mov_b32_e32 v74, 0
	s_cbranch_scc1 .LBB0_1113
	s_ashr_i32 s61, s60, 31
	s_add_u32 s66, s63, s60
	s_addc_u32 s67, s64, s61
	s_lshl_b64 s[66:67], s[66:67], 12
	v_lshl_add_u64 v[120:121], v[48:49], 0, s[66:67]
	global_load_ushort v74, v[120:121], off
.LBB0_1113:
	s_or_b32 s61, s59, 15
	s_ashr_i32 s62, s61, 31
	s_cmp_ge_i32 s61, s43
	s_cbranch_scc1 .LBB0_1115
	s_add_u32 s66, s63, s61
	s_addc_u32 s67, s64, s62
	s_lshl_b64 s[64:65], s[66:67], 12
	v_lshl_add_u64 v[120:121], v[48:49], 0, s[64:65]
	global_load_ushort v71, v[120:121], off

.LBB0_1155:
	s_add_i32 s6, s43, -3
	s_cmp_ge_i32 s6, s15
	v_mov_b32_e32 v45, 0
	s_cbranch_scc1 .LBB0_1157
	s_add_i32 s6, s6, s22
	s_ashr_i32 s7, s6, 31
	s_lshl_b64 s[6:7], s[6:7], 13
	v_lshl_add_u64 v[36:37], v[46:47], 0, s[6:7]
	global_load_dword v45, v[36:37], off

.LBB0_1161:
	s_add_i32 s6, s43, -2
	s_cmp_ge_i32 s6, s15
	v_mov_b32_e32 v60, 0
	s_cbranch_scc1 .LBB0_1163
	s_add_i32 s6, s6, s22
	s_ashr_i32 s7, s6, 31
	s_lshl_b64 s[6:7], s[6:7], 13
	v_lshl_add_u64 v[36:37], v[46:47], 0, s[6:7]
	global_load_dword v60, v[36:37], off

.LBB0_1167:
	s_cmp_gt_i32 s43, s15
	v_mov_b32_e32 v61, 0
	s_cbranch_scc1 .LBB0_1169
	s_add_i32 s6, s71, s43
	s_ashr_i32 s7, s6, 31
	s_lshl_b64 s[6:7], s[6:7], 13
	v_lshl_add_u64 v[36:37], v[46:47], 0, s[6:7]
	global_load_dword v61, v[36:37], off

.LBB0_1173:
	s_cmp_ge_i32 s43, s15
	v_mov_b32_e32 v62, 0
	s_cbranch_scc1 .LBB0_1175
	s_add_i32 s6, s43, s22
	s_ashr_i32 s7, s6, 31
	s_lshl_b64 s[6:7], s[6:7], 13
	v_lshl_add_u64 v[36:37], v[46:47], 0, s[6:7]
	global_load_dword v62, v[36:37], off

.LBB0_1179:
	s_add_i32 s6, s43, 1
	s_cmp_ge_i32 s6, s15
	v_mov_b32_e32 v63, 0
	s_cbranch_scc1 .LBB0_1181
	s_add_i32 s6, s6, s22
	s_ashr_i32 s7, s6, 31
	s_lshl_b64 s[6:7], s[6:7], 13
	v_lshl_add_u64 v[36:37], v[46:47], 0, s[6:7]
	global_load_dword v63, v[36:37], off

.LBB0_1185:
	s_add_i32 s6, s43, 2
	s_cmp_ge_i32 s6, s15
	v_mov_b32_e32 v64, 0
	s_cbranch_scc1 .LBB0_1187
	s_add_i32 s6, s6, s22
	s_ashr_i32 s7, s6, 31
	s_lshl_b64 s[6:7], s[6:7], 13
	v_lshl_add_u64 v[36:37], v[46:47], 0, s[6:7]
	global_load_dword v64, v[36:37], off

.LBB0_1191:
	s_add_i32 s6, s43, 3
	s_cmp_ge_i32 s6, s15
	v_mov_b32_e32 v65, 0
	s_cbranch_scc1 .LBB0_1193
	s_add_i32 s6, s6, s22
	s_ashr_i32 s7, s6, 31
	s_lshl_b64 s[6:7], s[6:7], 13
	v_lshl_add_u64 v[36:37], v[46:47], 0, s[6:7]
	global_load_dword v65, v[36:37], off

.LBB0_1197:
	s_add_i32 s6, s43, 4
	s_cmp_ge_i32 s6, s15
	v_mov_b32_e32 v66, 0
	s_cbranch_scc1 .LBB0_1199
	s_add_i32 s6, s6, s22
	s_ashr_i32 s7, s6, 31
	s_lshl_b64 s[6:7], s[6:7], 13
	v_lshl_add_u64 v[36:37], v[46:47], 0, s[6:7]
	global_load_dword v66, v[36:37], off

.LBB0_1203:
	s_add_i32 s6, s43, 5
	s_cmp_ge_i32 s6, s15
	v_mov_b32_e32 v67, 0
	s_cbranch_scc1 .LBB0_1205
	s_add_i32 s6, s6, s22
	s_ashr_i32 s7, s6, 31
	s_lshl_b64 s[6:7], s[6:7], 13
	v_lshl_add_u64 v[36:37], v[46:47], 0, s[6:7]
	global_load_dword v67, v[36:37], off

.LBB0_1209:
	s_add_i32 s6, s43, 6
	s_cmp_ge_i32 s6, s15
	v_mov_b32_e32 v68, 0
	s_cbranch_scc1 .LBB0_1211
	s_add_i32 s6, s6, s22
	s_ashr_i32 s7, s6, 31
	s_lshl_b64 s[6:7], s[6:7], 13
	v_lshl_add_u64 v[36:37], v[46:47], 0, s[6:7]
	global_load_dword v68, v[36:37], off

.LBB0_1215:
	s_add_i32 s6, s43, 7
	s_cmp_ge_i32 s6, s15
	v_mov_b32_e32 v69, 0
	s_cbranch_scc1 .LBB0_1217
	s_add_i32 s6, s6, s22
	s_ashr_i32 s7, s6, 31
	s_lshl_b64 s[6:7], s[6:7], 13
	v_lshl_add_u64 v[36:37], v[46:47], 0, s[6:7]
	global_load_dword v69, v[36:37], off

.LBB0_1221:
	s_add_i32 s6, s43, 8
	s_cmp_ge_i32 s6, s15
	v_mov_b32_e32 v70, 0
	s_cbranch_scc1 .LBB0_1223
	s_add_i32 s6, s6, s22
	s_ashr_i32 s7, s6, 31
	s_lshl_b64 s[6:7], s[6:7], 13
	v_lshl_add_u64 v[36:37], v[46:47], 0, s[6:7]
	global_load_dword v70, v[36:37], off

.LBB0_1227:
	s_add_i32 s6, s43, 9
	s_cmp_ge_i32 s6, s15
	v_mov_b32_e32 v82, 0
	s_cbranch_scc1 .LBB0_1229
	s_add_i32 s6, s6, s22
	s_ashr_i32 s7, s6, 31
	s_lshl_b64 s[6:7], s[6:7], 13
	v_lshl_add_u64 v[36:37], v[46:47], 0, s[6:7]
	global_load_dword v82, v[36:37], off

.LBB0_1233:
	s_add_i32 s6, s43, 10
	s_cmp_ge_i32 s6, s15
	v_mov_b32_e32 v88, 0
	s_cbranch_scc1 .LBB0_1235
	s_add_i32 s6, s6, s22
	s_ashr_i32 s7, s6, 31
	s_lshl_b64 s[6:7], s[6:7], 13
	v_lshl_add_u64 v[36:37], v[46:47], 0, s[6:7]
	global_load_dword v88, v[36:37], off

.LBB0_1239:
	s_add_i32 s6, s43, 11
	s_cmp_ge_i32 s6, s15
	v_mov_b32_e32 v98, 0
	s_cbranch_scc1 .LBB0_1241
	s_add_i32 s6, s6, s22
	s_ashr_i32 s7, s6, 31
	s_lshl_b64 s[6:7], s[6:7], 13
	v_lshl_add_u64 v[36:37], v[46:47], 0, s[6:7]
	global_load_dword v98, v[36:37], off

.LBB0_1245:
	s_add_i32 s6, s43, 12
	s_cmp_ge_i32 s6, s15
	v_mov_b32_e32 v145, 0
	s_cbranch_scc1 .LBB0_1247
	s_add_i32 s6, s6, s22
	s_ashr_i32 s7, s6, 31
	s_lshl_b64 s[6:7], s[6:7], 13
	v_lshl_add_u64 v[36:37], v[46:47], 0, s[6:7]
	global_load_dword v145, v[36:37], off

.LBB0_1251:
	s_add_i32 s6, s43, 13
	s_cmp_ge_i32 s6, s15
	v_mov_b32_e32 v146, 0
	s_cbranch_scc1 .LBB0_1253
	s_add_i32 s6, s6, s22
	s_ashr_i32 s7, s6, 31
	s_lshl_b64 s[6:7], s[6:7], 13
	v_lshl_add_u64 v[36:37], v[46:47], 0, s[6:7]
	global_load_dword v146, v[36:37], off

.LBB0_1257:
	s_add_i32 s6, s43, 14
	s_cmp_ge_i32 s6, s15
	v_mov_b32_e32 v147, 0
	s_cbranch_scc1 .LBB0_1259
	s_add_i32 s6, s6, s22
	s_ashr_i32 s7, s6, 31
	s_lshl_b64 s[6:7], s[6:7], 13
	v_lshl_add_u64 v[36:37], v[46:47], 0, s[6:7]
	global_load_dword v147, v[36:37], off

.LBB0_1263:
	s_add_i32 s6, s43, 15
	s_cmp_ge_i32 s6, s15
	v_mov_b32_e32 v148, 0
	s_cbranch_scc1 .LBB0_1265
	s_add_i32 s6, s6, s22
	s_ashr_i32 s7, s6, 31
	s_lshl_b64 s[6:7], s[6:7], 13
	v_lshl_add_u64 v[36:37], v[46:47], 0, s[6:7]
	global_load_dword v148, v[36:37], off

.LBB0_1285:
	s_add_u32 s6, s6, s61
	s_addc_u32 s7, s7, s62
	s_lshl_b64 s[6:7], s[6:7], 12
	v_lshl_add_u64 v[36:37], v[48:49], 0, s[6:7]
	global_load_ushort v163, v[36:37], off
.LBB0_1286:
	ds_read_b128 v[184:187], v144
	ds_read_b128 v[188:191], v144 offset:64
	ds_read_b128 v[192:195], v144 offset:128
	ds_read_b128 v[196:199], v144 offset:192
	ds_read_b32 v200, v128 offset:17408
	ds_read_b32 v204, v129 offset:17408
	ds_read_b32 v208, v130 offset:17408
	ds_read_b32 v212, v131 offset:17408
	s_nop 0
	s_nop 0
	s_lshl_b32 s59, s59, 6
	s_sub_i32 s6, s15, s59
	s_min_i32 s70, s6, 64
	s_waitcnt lgkmcnt(8)
	s_waitcnt lgkmcnt(7)
	v_mfma_f32_16x16x32_bf16 v[40:43], v[184:187], v[2:5], 0
	v_mfma_f32_16x16x32_bf16 v[36:39], v[184:187], v[6:9], 0
	ds_read_b128 v[184:187], v144 offset:4352
	s_waitcnt lgkmcnt(7)
	v_mfma_f32_16x16x32_bf16 v[40:43], v[188:191], v[10:13], v[40:43]
	v_mfma_f32_16x16x32_bf16 v[36:39], v[188:191], v[14:17], v[36:39]
	ds_read_b128 v[188:191], v144 offset:4416
	s_nop 0
	s_nop 0
	s_waitcnt lgkmcnt(7)
	v_mfma_f32_16x16x32_bf16 v[40:43], v[192:195], v[18:21], v[40:43]
	v_mfma_f32_16x16x32_bf16 v[36:39], v[192:195], v[22:25], v[36:39]
	ds_read_b128 v[192:195], v144 offset:4480
	s_nop 0
	s_nop 0
	s_waitcnt lgkmcnt(7)
	v_mfma_f32_16x16x32_bf16 v[40:43], v[196:199], v[26:29], v[40:43]
	s_nop 7
	v_add_f32_e32 v1, v52, v40
	v_mul_f32_e32 v1, 0xbfb8aa3b, v1
	v_exp_f32_e32 v1, v1
	v_mfma_f32_16x16x32_bf16 v[36:39], v[196:199], v[30:33], v[36:39]
	ds_read_b128 v[196:199], v144 offset:4544
	v_add_f32_e32 v1, 1.0, v1
	v_rcp_f32_e32 v1, v1
	s_nop 0
	v_mul_f32_e32 v1, v89, v1
	v_mul_f32_e32 v40, 0x3fb8aa3b, v1
	v_exp_f32_e32 v40, v40
	v_add_f32_e32 v174, v1, v1
	v_cmp_nlt_f32_e32 vcc, s33, v174
	s_and_saveexec_b64 s[6:7], vcc
	s_xor_b64 s[6:7], exec, s[6:7]
	v_fma_f32 v173, -v40, v40, 1.0
	s_andn2_saveexec_b64 s[6:7], s[6:7]
	v_fmamk_f32 v1, v174, 0x3d2aaaab, v225
	v_fma_f32 v1, v174, v1, 0.5
	v_fma_f32 v1, v174, v1, 1.0
	v_mul_f32_e64 v173, v1, -v174
	s_or_b64 exec, exec, s[6:7]
	v_add_f32_e32 v1, v53, v36
	v_mul_f32_e32 v1, 0xbfb8aa3b, v1
	v_exp_f32_e32 v1, v1
	v_max_f32_e32 v36, v173, v173
	v_max_f32_e32 v36, 0, v36
	v_sqrt_f32_e32 v36, v36
	v_add_f32_e32 v1, 1.0, v1
	v_rcp_f32_e32 v1, v1
	v_cmp_gt_i32_e32 vcc, s70, v92
	v_mul_f32_e32 v1, v1, v36
	s_nop 0
	s_nop 0
	s_waitcnt lgkmcnt(7)
	v_mul_f32_e32 v1, v200, v1
	ds_read_b32 v200, v132 offset:17408
	v_cndmask_b32_e32 v36, 1.0, v40, vcc
	v_cndmask_b32_e32 v1, 0, v1, vcc
	ds_write_b32 v128, v36 offset:50176
	v_add_u32_e32 v36, 0x14400, v128
	ds_write_b32 v36, v1
	v_add_f32_e32 v1, v52, v41
	v_mul_f32_e32 v1, 0xbfb8aa3b, v1
	v_exp_f32_e32 v1, v1
	s_nop 0
	v_add_f32_e32 v1, 1.0, v1
	v_rcp_f32_e32 v1, v1
	s_nop 0
	v_mul_f32_e32 v1, v89, v1
	v_mul_f32_e32 v36, 0x3fb8aa3b, v1
	v_exp_f32_e32 v36, v36
	v_add_f32_e32 v41, v1, v1
	v_cmp_nlt_f32_e32 vcc, s33, v41
	s_and_saveexec_b64 s[6:7], vcc
	s_xor_b64 s[6:7], exec, s[6:7]
	v_fma_f32 v40, -v36, v36, 1.0
	s_andn2_saveexec_b64 s[6:7], s[6:7]
	v_fmamk_f32 v1, v41, 0x3d2aaaab, v225
	v_fma_f32 v1, v41, v1, 0.5
	v_fma_f32 v1, v41, v1, 1.0
	v_mul_f32_e64 v40, v1, -v41
	s_or_b64 exec, exec, s[6:7]
	v_add_f32_e32 v1, v53, v37
	v_mul_f32_e32 v1, 0xbfb8aa3b, v1
	v_exp_f32_e32 v1, v1
	v_max_f32_e32 v37, v40, v40
	v_max_f32_e32 v37, 0, v37
	v_sqrt_f32_e32 v37, v37
	v_add_f32_e32 v1, 1.0, v1
	v_rcp_f32_e32 v1, v1
	v_cmp_gt_i32_e32 vcc, s70, v94
	v_mul_f32_e32 v1, v1, v37
	s_nop 0
	v_cndmask_b32_e32 v36, 1.0, v36, vcc
	ds_write_b32 v129, v36 offset:50176
	v_add_u32_e32 v36, 0x14400, v129
	s_nop 0
	s_waitcnt lgkmcnt(10)
	v_mul_f32_e32 v1, v204, v1
	ds_read_b32 v204, v133 offset:17408
	v_cndmask_b32_e32 v1, 0, v1, vcc
	ds_write_b32 v36, v1
	v_add_f32_e32 v1, v52, v42
	v_mul_f32_e32 v1, 0xbfb8aa3b, v1
	v_exp_f32_e32 v1, v1
	s_nop 0
	v_add_f32_e32 v1, 1.0, v1
	v_rcp_f32_e32 v1, v1
	s_nop 0
	v_mul_f32_e32 v1, v89, v1
	v_mul_f32_e32 v36, 0x3fb8aa3b, v1
	v_exp_f32_e32 v36, v36
	v_add_f32_e32 v40, v1, v1
	v_cmp_nlt_f32_e32 vcc, s33, v40
	s_and_saveexec_b64 s[6:7], vcc
	s_xor_b64 s[6:7], exec, s[6:7]
	v_fma_f32 v37, -v36, v36, 1.0
	s_andn2_saveexec_b64 s[6:7], s[6:7]
	v_fmamk_f32 v1, v40, 0x3d2aaaab, v225
	v_fma_f32 v1, v40, v1, 0.5
	v_fma_f32 v1, v40, v1, 1.0
	v_mul_f32_e64 v37, v1, -v40
	s_or_b64 exec, exec, s[6:7]
	v_add_f32_e32 v1, v53, v38
	v_mul_f32_e32 v1, 0xbfb8aa3b, v1
	v_exp_f32_e32 v1, v1
	v_max_f32_e32 v37, v37, v37
	v_max_f32_e32 v37, 0, v37
	v_sqrt_f32_e32 v37, v37
	v_add_f32_e32 v1, 1.0, v1
	v_rcp_f32_e32 v1, v1
	v_cmp_gt_i32_e32 vcc, s70, v95
	v_mul_f32_e32 v1, v1, v37
	s_nop 0
	v_cndmask_b32_e32 v36, 1.0, v36, vcc
	ds_write_b32 v130, v36 offset:50176
	v_add_u32_e32 v36, 0x14400, v130
	s_nop 0
	s_waitcnt lgkmcnt(12)
	v_mul_f32_e32 v1, v208, v1
	ds_read_b32 v208, v134 offset:17408
	v_cndmask_b32_e32 v1, 0, v1, vcc
	ds_write_b32 v36, v1
	v_add_f32_e32 v1, v52, v43
	v_mul_f32_e32 v1, 0xbfb8aa3b, v1
	v_exp_f32_e32 v1, v1
	s_nop 0
	v_add_f32_e32 v1, 1.0, v1
	v_rcp_f32_e32 v1, v1
	s_nop 0
	v_mul_f32_e32 v1, v89, v1
	v_mul_f32_e32 v36, 0x3fb8aa3b, v1
	v_exp_f32_e32 v36, v36
	v_add_f32_e32 v38, v1, v1
	v_cmp_nlt_f32_e32 vcc, s33, v38
	s_and_saveexec_b64 s[6:7], vcc
	s_xor_b64 s[6:7], exec, s[6:7]
	v_fma_f32 v37, -v36, v36, 1.0
	s_andn2_saveexec_b64 s[6:7], s[6:7]
	v_fmamk_f32 v1, v38, 0x3d2aaaab, v225
	v_fma_f32 v1, v38, v1, 0.5
	v_fma_f32 v1, v38, v1, 1.0
	v_mul_f32_e64 v37, v1, -v38
	s_or_b64 exec, exec, s[6:7]
	v_add_f32_e32 v1, v53, v39
	v_mul_f32_e32 v1, 0xbfb8aa3b, v1
	v_exp_f32_e32 v1, v1
	v_max_f32_e32 v37, v37, v37
	v_max_f32_e32 v37, 0, v37
	v_sqrt_f32_e32 v37, v37
	v_add_f32_e32 v1, 1.0, v1
	v_rcp_f32_e32 v1, v1
	v_cmp_gt_i32_e32 vcc, s70, v96
	v_mul_f32_e32 v1, v1, v37
	s_nop 0
	v_cndmask_b32_e32 v36, 1.0, v36, vcc
	ds_write_b32 v131, v36 offset:50176
	v_add_u32_e32 v36, 0x14400, v131
	s_nop 0
	s_waitcnt lgkmcnt(14)
	v_mul_f32_e32 v1, v212, v1
	ds_read_b32 v212, v135 offset:17408
	v_cndmask_b32_e32 v1, 0, v1, vcc
	ds_write_b32 v36, v1
	s_nop 0
	s_nop 0
	s_nop 0
	s_waitcnt lgkmcnt(15)
	v_mfma_f32_16x16x32_bf16 v[40:43], v[184:187], v[2:5], 0
	v_mfma_f32_16x16x32_bf16 v[36:39], v[184:187], v[6:9], 0
	ds_read_b128 v[184:187], v144 offset:8704
	s_waitcnt lgkmcnt(15)
	v_mfma_f32_16x16x32_bf16 v[40:43], v[188:191], v[10:13], v[40:43]
	v_mfma_f32_16x16x32_bf16 v[36:39], v[188:191], v[14:17], v[36:39]
	ds_read_b128 v[188:191], v144 offset:8768
	s_nop 0
	s_nop 0
	s_waitcnt lgkmcnt(15)
	v_mfma_f32_16x16x32_bf16 v[40:43], v[192:195], v[18:21], v[40:43]
	v_mfma_f32_16x16x32_bf16 v[36:39], v[192:195], v[22:25], v[36:39]
	ds_read_b128 v[192:195], v144 offset:8832
	s_nop 0
	s_nop 0
	s_waitcnt lgkmcnt(15)
	v_mfma_f32_16x16x32_bf16 v[40:43], v[196:199], v[26:29], v[40:43]
	s_nop 7
	v_add_f32_e32 v1, v52, v40
	v_mul_f32_e32 v1, 0xbfb8aa3b, v1
	v_exp_f32_e32 v1, v1
	v_mfma_f32_16x16x32_bf16 v[36:39], v[196:199], v[30:33], v[36:39]
	ds_read_b128 v[196:199], v144 offset:8896
	v_add_f32_e32 v1, 1.0, v1
	v_rcp_f32_e32 v1, v1
	s_nop 0
	v_mul_f32_e32 v1, v89, v1
	v_mul_f32_e32 v40, 0x3fb8aa3b, v1
	v_exp_f32_e32 v40, v40
	v_add_f32_e32 v174, v1, v1
	v_cmp_nlt_f32_e32 vcc, s33, v174
	s_and_saveexec_b64 s[6:7], vcc
	s_xor_b64 s[6:7], exec, s[6:7]
	v_fma_f32 v173, -v40, v40, 1.0
	s_andn2_saveexec_b64 s[6:7], s[6:7]
	v_fmamk_f32 v1, v174, 0x3d2aaaab, v225
	v_fma_f32 v1, v174, v1, 0.5
	v_fma_f32 v1, v174, v1, 1.0
	v_mul_f32_e64 v173, v1, -v174
	s_or_b64 exec, exec, s[6:7]
	v_add_f32_e32 v1, v53, v36
	v_mul_f32_e32 v1, 0xbfb8aa3b, v1
	v_exp_f32_e32 v1, v1
	v_max_f32_e32 v36, v173, v173
	v_max_f32_e32 v36, 0, v36
	v_sqrt_f32_e32 v36, v36
	v_add_f32_e32 v1, 1.0, v1
	v_rcp_f32_e32 v1, v1
	v_cmp_gt_i32_e32 vcc, s70, v97
	v_mul_f32_e32 v1, v1, v36
	s_nop 0
	s_nop 0
	s_waitcnt lgkmcnt(15)
	v_mul_f32_e32 v1, v200, v1
	ds_read_b32 v200, v136 offset:17408
	v_cndmask_b32_e32 v36, 1.0, v40, vcc
	v_cndmask_b32_e32 v1, 0, v1, vcc
	ds_write_b32 v132, v36 offset:50176
	v_add_u32_e32 v36, 0x14400, v132
	ds_write_b32 v36, v1
	v_add_f32_e32 v1, v52, v41
	v_mul_f32_e32 v1, 0xbfb8aa3b, v1
	v_exp_f32_e32 v1, v1
	s_nop 0
	v_add_f32_e32 v1, 1.0, v1
	v_rcp_f32_e32 v1, v1
	s_nop 0
	v_mul_f32_e32 v1, v89, v1
	v_mul_f32_e32 v36, 0x3fb8aa3b, v1
	v_exp_f32_e32 v36, v36
	v_add_f32_e32 v41, v1, v1
	v_cmp_nlt_f32_e32 vcc, s33, v41
	s_and_saveexec_b64 s[6:7], vcc
	s_xor_b64 s[6:7], exec, s[6:7]
	v_fma_f32 v40, -v36, v36, 1.0
	s_andn2_saveexec_b64 s[6:7], s[6:7]
	v_fmamk_f32 v1, v41, 0x3d2aaaab, v225
	v_fma_f32 v1, v41, v1, 0.5
	v_fma_f32 v1, v41, v1, 1.0
	v_mul_f32_e64 v40, v1, -v41
	s_or_b64 exec, exec, s[6:7]
	v_add_f32_e32 v1, v53, v37
	v_mul_f32_e32 v1, 0xbfb8aa3b, v1
	v_exp_f32_e32 v1, v1
	v_max_f32_e32 v37, v40, v40
	v_max_f32_e32 v37, 0, v37
	v_sqrt_f32_e32 v37, v37
	v_add_f32_e32 v1, 1.0, v1
	v_rcp_f32_e32 v1, v1
	v_cmp_gt_i32_e32 vcc, s70, v99
	v_mul_f32_e32 v1, v1, v37
	s_nop 0
	v_cndmask_b32_e32 v36, 1.0, v36, vcc
	ds_write_b32 v133, v36 offset:50176
	v_add_u32_e32 v36, 0x14400, v133
	s_nop 0
	s_waitcnt lgkmcnt(15)
	v_mul_f32_e32 v1, v204, v1
	ds_read_b32 v204, v137 offset:17408
	v_cndmask_b32_e32 v1, 0, v1, vcc
	ds_write_b32 v36, v1
	v_add_f32_e32 v1, v52, v42
	v_mul_f32_e32 v1, 0xbfb8aa3b, v1
	v_exp_f32_e32 v1, v1
	s_nop 0
	v_add_f32_e32 v1, 1.0, v1
	v_rcp_f32_e32 v1, v1
	s_nop 0
	v_mul_f32_e32 v1, v89, v1
	v_mul_f32_e32 v36, 0x3fb8aa3b, v1
	v_exp_f32_e32 v36, v36
	v_add_f32_e32 v40, v1, v1
	v_cmp_nlt_f32_e32 vcc, s33, v40
	s_and_saveexec_b64 s[6:7], vcc
	s_xor_b64 s[6:7], exec, s[6:7]
	v_fma_f32 v37, -v36, v36, 1.0
	s_andn2_saveexec_b64 s[6:7], s[6:7]
	v_fmamk_f32 v1, v40, 0x3d2aaaab, v225
	v_fma_f32 v1, v40, v1, 0.5
	v_fma_f32 v1, v40, v1, 1.0
	v_mul_f32_e64 v37, v1, -v40
	s_or_b64 exec, exec, s[6:7]
	v_add_f32_e32 v1, v53, v38
	v_mul_f32_e32 v1, 0xbfb8aa3b, v1
	v_exp_f32_e32 v1, v1
	v_max_f32_e32 v37, v37, v37
	v_max_f32_e32 v37, 0, v37
	v_sqrt_f32_e32 v37, v37
	v_add_f32_e32 v1, 1.0, v1
	v_rcp_f32_e32 v1, v1
	v_cmp_gt_i32_e32 vcc, s70, v100
	v_mul_f32_e32 v1, v1, v37
	s_nop 0
	v_cndmask_b32_e32 v36, 1.0, v36, vcc
	ds_write_b32 v134, v36 offset:50176
	v_add_u32_e32 v36, 0x14400, v134
	s_nop 0
	s_waitcnt lgkmcnt(15)
	v_mul_f32_e32 v1, v208, v1
	ds_read_b32 v208, v138 offset:17408
	v_cndmask_b32_e32 v1, 0, v1, vcc
	ds_write_b32 v36, v1
	v_add_f32_e32 v1, v52, v43
	v_mul_f32_e32 v1, 0xbfb8aa3b, v1
	v_exp_f32_e32 v1, v1
	s_nop 0
	v_add_f32_e32 v1, 1.0, v1
	v_rcp_f32_e32 v1, v1
	s_nop 0
	v_mul_f32_e32 v1, v89, v1
	v_mul_f32_e32 v36, 0x3fb8aa3b, v1
	v_exp_f32_e32 v36, v36
	v_add_f32_e32 v38, v1, v1
	v_cmp_nlt_f32_e32 vcc, s33, v38
	s_and_saveexec_b64 s[6:7], vcc
	s_xor_b64 s[6:7], exec, s[6:7]
	v_fma_f32 v37, -v36, v36, 1.0
	s_andn2_saveexec_b64 s[6:7], s[6:7]
	v_fmamk_f32 v1, v38, 0x3d2aaaab, v225
	v_fma_f32 v1, v38, v1, 0.5
	v_fma_f32 v1, v38, v1, 1.0
	v_mul_f32_e64 v37, v1, -v38
	s_or_b64 exec, exec, s[6:7]
	v_add_f32_e32 v1, v53, v39
	v_mul_f32_e32 v1, 0xbfb8aa3b, v1
	v_exp_f32_e32 v1, v1
	v_max_f32_e32 v37, v37, v37
	v_max_f32_e32 v37, 0, v37
	v_sqrt_f32_e32 v37, v37
	v_add_f32_e32 v1, 1.0, v1
	v_rcp_f32_e32 v1, v1
	v_cmp_gt_i32_e32 vcc, s70, v101
	v_mul_f32_e32 v1, v1, v37
	s_nop 0
	v_cndmask_b32_e32 v36, 1.0, v36, vcc
	ds_write_b32 v135, v36 offset:50176
	v_add_u32_e32 v36, 0x14400, v135
	s_nop 0
	s_waitcnt lgkmcnt(15)
	v_mul_f32_e32 v1, v212, v1
	ds_read_b32 v212, v139 offset:17408
	v_cndmask_b32_e32 v1, 0, v1, vcc
	ds_write_b32 v36, v1
	s_nop 0
	s_nop 0
	s_nop 0
	s_waitcnt lgkmcnt(15)
	v_mfma_f32_16x16x32_bf16 v[40:43], v[184:187], v[2:5], 0
	v_mfma_f32_16x16x32_bf16 v[36:39], v[184:187], v[6:9], 0
	ds_read_b128 v[184:187], v144 offset:13056
	s_waitcnt lgkmcnt(15)
	v_mfma_f32_16x16x32_bf16 v[40:43], v[188:191], v[10:13], v[40:43]
	v_mfma_f32_16x16x32_bf16 v[36:39], v[188:191], v[14:17], v[36:39]
	ds_read_b128 v[188:191], v144 offset:13120
	s_nop 0
	s_nop 0
	s_waitcnt lgkmcnt(15)
	v_mfma_f32_16x16x32_bf16 v[40:43], v[192:195], v[18:21], v[40:43]
	v_mfma_f32_16x16x32_bf16 v[36:39], v[192:195], v[22:25], v[36:39]
	ds_read_b128 v[192:195], v144 offset:13184
	s_nop 0
	s_nop 0
	s_waitcnt lgkmcnt(15)
	v_mfma_f32_16x16x32_bf16 v[40:43], v[196:199], v[26:29], v[40:43]
	s_nop 7
	v_add_f32_e32 v1, v52, v40
	v_mul_f32_e32 v1, 0xbfb8aa3b, v1
	v_exp_f32_e32 v1, v1
	v_mfma_f32_16x16x32_bf16 v[36:39], v[196:199], v[30:33], v[36:39]
	v_add_f32_e32 v1, 1.0, v1
	v_rcp_f32_e32 v1, v1
	s_nop 0
	v_mul_f32_e32 v1, v89, v1
	v_mul_f32_e32 v40, 0x3fb8aa3b, v1
	v_exp_f32_e32 v40, v40
	v_add_f32_e32 v174, v1, v1
	v_cmp_nlt_f32_e32 vcc, s33, v174
	s_and_saveexec_b64 s[6:7], vcc
	s_xor_b64 s[6:7], exec, s[6:7]
	v_fma_f32 v173, -v40, v40, 1.0
	s_andn2_saveexec_b64 s[6:7], s[6:7]
	v_fmamk_f32 v1, v174, 0x3d2aaaab, v225
	v_fma_f32 v1, v174, v1, 0.5
	v_fma_f32 v1, v174, v1, 1.0
	v_mul_f32_e64 v173, v1, -v174
	s_or_b64 exec, exec, s[6:7]
	v_add_f32_e32 v1, v53, v36
	v_mul_f32_e32 v1, 0xbfb8aa3b, v1
	v_exp_f32_e32 v1, v1
	v_max_f32_e32 v36, v173, v173
	v_max_f32_e32 v36, 0, v36
	v_sqrt_f32_e32 v36, v36
	v_add_f32_e32 v1, 1.0, v1
	v_rcp_f32_e32 v1, v1
	v_cmp_gt_i32_e32 vcc, s70, v102
	v_mul_f32_e32 v1, v1, v36
	s_nop 0
	s_nop 0
	s_waitcnt lgkmcnt(14)
	v_mul_f32_e32 v1, v200, v1
	v_cndmask_b32_e32 v36, 1.0, v40, vcc
	v_cndmask_b32_e32 v1, 0, v1, vcc
	ds_write_b32 v136, v36 offset:50176
	v_add_u32_e32 v36, 0x14400, v136
	ds_write_b32 v36, v1
	v_add_f32_e32 v1, v52, v41
	v_mul_f32_e32 v1, 0xbfb8aa3b, v1
	v_exp_f32_e32 v1, v1
	s_nop 0
	v_add_f32_e32 v1, 1.0, v1
	v_rcp_f32_e32 v1, v1
	s_nop 0
	v_mul_f32_e32 v1, v89, v1
	v_mul_f32_e32 v36, 0x3fb8aa3b, v1
	v_exp_f32_e32 v36, v36
	v_add_f32_e32 v41, v1, v1
	v_cmp_nlt_f32_e32 vcc, s33, v41
	s_and_saveexec_b64 s[6:7], vcc
	s_xor_b64 s[6:7], exec, s[6:7]
	v_fma_f32 v40, -v36, v36, 1.0
	s_andn2_saveexec_b64 s[6:7], s[6:7]
	v_fmamk_f32 v1, v41, 0x3d2aaaab, v225
	v_fma_f32 v1, v41, v1, 0.5
	v_fma_f32 v1, v41, v1, 1.0
	v_mul_f32_e64 v40, v1, -v41
	s_or_b64 exec, exec, s[6:7]
	v_add_f32_e32 v1, v53, v37
	v_mul_f32_e32 v1, 0xbfb8aa3b, v1
	v_exp_f32_e32 v1, v1
	v_max_f32_e32 v37, v40, v40
	v_max_f32_e32 v37, 0, v37
	v_sqrt_f32_e32 v37, v37
	v_add_f32_e32 v1, 1.0, v1
	v_rcp_f32_e32 v1, v1
	v_cmp_gt_i32_e32 vcc, s70, v103
	v_mul_f32_e32 v1, v1, v37
	s_nop 0
	v_cndmask_b32_e32 v36, 1.0, v36, vcc
	ds_write_b32 v137, v36 offset:50176
	v_add_u32_e32 v36, 0x14400, v137
	s_nop 0
	s_waitcnt lgkmcnt(13)
	v_mul_f32_e32 v1, v204, v1
	v_cndmask_b32_e32 v1, 0, v1, vcc
	ds_write_b32 v36, v1
	v_add_f32_e32 v1, v52, v42
	v_mul_f32_e32 v1, 0xbfb8aa3b, v1
	v_exp_f32_e32 v1, v1
	s_nop 0
	v_add_f32_e32 v1, 1.0, v1
	v_rcp_f32_e32 v1, v1
	s_nop 0
	v_mul_f32_e32 v1, v89, v1
	v_mul_f32_e32 v36, 0x3fb8aa3b, v1
	v_exp_f32_e32 v36, v36
	v_add_f32_e32 v40, v1, v1
	v_cmp_nlt_f32_e32 vcc, s33, v40
	s_and_saveexec_b64 s[6:7], vcc
	s_xor_b64 s[6:7], exec, s[6:7]
	v_fma_f32 v37, -v36, v36, 1.0
	s_andn2_saveexec_b64 s[6:7], s[6:7]
	v_fmamk_f32 v1, v40, 0x3d2aaaab, v225
	v_fma_f32 v1, v40, v1, 0.5
	v_fma_f32 v1, v40, v1, 1.0
	v_mul_f32_e64 v37, v1, -v40
	s_or_b64 exec, exec, s[6:7]
	v_add_f32_e32 v1, v53, v38
	v_mul_f32_e32 v1, 0xbfb8aa3b, v1
	v_exp_f32_e32 v1, v1
	v_max_f32_e32 v37, v37, v37
	v_max_f32_e32 v37, 0, v37
	v_sqrt_f32_e32 v37, v37
	v_add_f32_e32 v1, 1.0, v1
	v_rcp_f32_e32 v1, v1
	v_cmp_gt_i32_e32 vcc, s70, v104
	v_mul_f32_e32 v1, v1, v37
	s_nop 0
	v_cndmask_b32_e32 v36, 1.0, v36, vcc
	ds_write_b32 v138, v36 offset:50176
	v_add_u32_e32 v36, 0x14400, v138
	s_nop 0
	s_waitcnt lgkmcnt(12)
	v_mul_f32_e32 v1, v208, v1
	v_cndmask_b32_e32 v1, 0, v1, vcc
	ds_write_b32 v36, v1
	v_add_f32_e32 v1, v52, v43
	v_mul_f32_e32 v1, 0xbfb8aa3b, v1
	v_exp_f32_e32 v1, v1
	s_nop 0
	v_add_f32_e32 v1, 1.0, v1
	v_rcp_f32_e32 v1, v1
	s_nop 0
	v_mul_f32_e32 v1, v89, v1
	v_mul_f32_e32 v36, 0x3fb8aa3b, v1
	v_exp_f32_e32 v36, v36
	v_add_f32_e32 v38, v1, v1
	v_cmp_nlt_f32_e32 vcc, s33, v38
	s_and_saveexec_b64 s[6:7], vcc
	s_xor_b64 s[6:7], exec, s[6:7]
	v_fma_f32 v37, -v36, v36, 1.0
	s_andn2_saveexec_b64 s[6:7], s[6:7]
	v_fmamk_f32 v1, v38, 0x3d2aaaab, v225
	v_fma_f32 v1, v38, v1, 0.5
	v_fma_f32 v1, v38, v1, 1.0
	v_mul_f32_e64 v37, v1, -v38
	s_or_b64 exec, exec, s[6:7]
	v_add_f32_e32 v1, v53, v39
	v_mul_f32_e32 v1, 0xbfb8aa3b, v1
	v_exp_f32_e32 v1, v1
	v_max_f32_e32 v37, v37, v37
	v_max_f32_e32 v37, 0, v37
	v_sqrt_f32_e32 v37, v37
	v_add_f32_e32 v1, 1.0, v1
	v_rcp_f32_e32 v1, v1
	v_cmp_gt_i32_e32 vcc, s70, v105
	v_mul_f32_e32 v1, v1, v37
	s_nop 0
	v_cndmask_b32_e32 v36, 1.0, v36, vcc
	ds_write_b32 v139, v36 offset:50176
	v_add_u32_e32 v36, 0x14400, v139
	s_nop 0
	s_waitcnt lgkmcnt(11)
	v_mul_f32_e32 v1, v212, v1
	v_cndmask_b32_e32 v1, 0, v1, vcc
	ds_write_b32 v36, v1
	s_nop 0
	s_nop 0
	s_nop 0
	s_waitcnt lgkmcnt(10)
	v_mfma_f32_16x16x32_bf16 v[40:43], v[184:187], v[2:5], 0
	v_mfma_f32_16x16x32_bf16 v[36:39], v[184:187], v[6:9], 0
	s_waitcnt lgkmcnt(9)
	v_mfma_f32_16x16x32_bf16 v[40:43], v[188:191], v[10:13], v[40:43]
	v_mfma_f32_16x16x32_bf16 v[36:39], v[188:191], v[14:17], v[36:39]
	s_nop 0
	s_nop 0
	s_waitcnt lgkmcnt(8)
	v_mfma_f32_16x16x32_bf16 v[40:43], v[192:195], v[18:21], v[40:43]
	v_mfma_f32_16x16x32_bf16 v[36:39], v[192:195], v[22:25], v[36:39]
	ds_read_b32 v184, v140 offset:17408
	ds_read_b32 v188, v141 offset:17408
	ds_read_b32 v192, v142 offset:17408
	ds_read_b128 v[174:177], v144 offset:13248
	s_nop 0
	s_waitcnt lgkmcnt(0)
	v_mfma_f32_16x16x32_bf16 v[40:43], v[174:177], v[26:29], v[40:43]
	s_nop 7
	v_add_f32_e32 v1, v52, v40
	v_mul_f32_e32 v1, 0xbfb8aa3b, v1
	v_exp_f32_e32 v1, v1
	v_mfma_f32_16x16x32_bf16 v[36:39], v[174:177], v[30:33], v[36:39]
	v_add_f32_e32 v1, 1.0, v1
	v_rcp_f32_e32 v1, v1
	s_nop 0
	v_mul_f32_e32 v1, v89, v1
	v_mul_f32_e32 v40, 0x3fb8aa3b, v1
	v_exp_f32_e32 v40, v40
	v_add_f32_e32 v174, v1, v1
	v_cmp_nlt_f32_e32 vcc, s33, v174
	s_and_saveexec_b64 s[6:7], vcc
	s_xor_b64 s[6:7], exec, s[6:7]
	v_fma_f32 v173, -v40, v40, 1.0
	s_andn2_saveexec_b64 s[6:7], s[6:7]
	v_fmamk_f32 v1, v174, 0x3d2aaaab, v225
	v_fma_f32 v1, v174, v1, 0.5
	v_fma_f32 v1, v174, v1, 1.0
	v_mul_f32_e64 v173, v1, -v174
	s_or_b64 exec, exec, s[6:7]
	v_add_f32_e32 v1, v53, v36
	v_mul_f32_e32 v1, 0xbfb8aa3b, v1
	v_exp_f32_e32 v1, v1
	v_max_f32_e32 v36, v173, v173
	v_max_f32_e32 v36, 0, v36
	v_sqrt_f32_e32 v36, v36
	v_add_f32_e32 v1, 1.0, v1
	v_rcp_f32_e32 v1, v1
	v_cmp_gt_i32_e32 vcc, s70, v106
	v_mul_f32_e32 v1, v1, v36
	s_nop 0
	s_nop 0
	v_mul_f32_e32 v1, v184, v1
	v_cndmask_b32_e32 v36, 1.0, v40, vcc
	v_cndmask_b32_e32 v1, 0, v1, vcc
	ds_write_b32 v140, v36 offset:50176
	v_add_u32_e32 v36, 0x14400, v140
	ds_write_b32 v36, v1
	v_add_f32_e32 v1, v52, v41
	v_mul_f32_e32 v1, 0xbfb8aa3b, v1
	v_exp_f32_e32 v1, v1
	s_nop 0
	v_add_f32_e32 v1, 1.0, v1
	v_rcp_f32_e32 v1, v1
	s_nop 0
	v_mul_f32_e32 v1, v89, v1
	v_mul_f32_e32 v36, 0x3fb8aa3b, v1
	v_exp_f32_e32 v36, v36
	v_add_f32_e32 v41, v1, v1
	v_cmp_nlt_f32_e32 vcc, s33, v41
	s_and_saveexec_b64 s[6:7], vcc
	s_xor_b64 s[6:7], exec, s[6:7]
	v_fma_f32 v40, -v36, v36, 1.0
	s_andn2_saveexec_b64 s[6:7], s[6:7]
	v_fmamk_f32 v1, v41, 0x3d2aaaab, v225
	v_fma_f32 v1, v41, v1, 0.5
	v_fma_f32 v1, v41, v1, 1.0
	v_mul_f32_e64 v40, v1, -v41
	s_or_b64 exec, exec, s[6:7]
	v_add_f32_e32 v1, v53, v37
	v_mul_f32_e32 v1, 0xbfb8aa3b, v1
	v_exp_f32_e32 v1, v1
	v_max_f32_e32 v37, v40, v40
	v_max_f32_e32 v37, 0, v37
	v_sqrt_f32_e32 v37, v37
	v_add_f32_e32 v1, 1.0, v1
	v_rcp_f32_e32 v1, v1
	v_cmp_gt_i32_e32 vcc, s70, v107
	v_mul_f32_e32 v1, v1, v37
	s_nop 0
	v_cndmask_b32_e32 v36, 1.0, v36, vcc
	ds_write_b32 v141, v36 offset:50176
	v_add_u32_e32 v36, 0x14400, v141
	s_nop 0
	v_mul_f32_e32 v1, v188, v1
	v_cndmask_b32_e32 v1, 0, v1, vcc
	ds_write_b32 v36, v1
	v_add_f32_e32 v1, v52, v42
	v_mul_f32_e32 v1, 0xbfb8aa3b, v1
	v_exp_f32_e32 v1, v1
	s_nop 0
	v_add_f32_e32 v1, 1.0, v1
	v_rcp_f32_e32 v1, v1
	s_nop 0
	v_mul_f32_e32 v1, v89, v1
	v_mul_f32_e32 v36, 0x3fb8aa3b, v1
	v_exp_f32_e32 v36, v36
	v_add_f32_e32 v40, v1, v1
	v_cmp_nlt_f32_e32 vcc, s33, v40
	s_and_saveexec_b64 s[6:7], vcc
	s_xor_b64 s[6:7], exec, s[6:7]
	v_fma_f32 v37, -v36, v36, 1.0
	s_andn2_saveexec_b64 s[6:7], s[6:7]
	v_fmamk_f32 v1, v40, 0x3d2aaaab, v225
	v_fma_f32 v1, v40, v1, 0.5
	v_fma_f32 v1, v40, v1, 1.0
	v_mul_f32_e64 v37, v1, -v40
	s_or_b64 exec, exec, s[6:7]
	v_add_f32_e32 v1, v53, v38
	v_mul_f32_e32 v1, 0xbfb8aa3b, v1
	v_exp_f32_e32 v1, v1
	v_max_f32_e32 v37, v37, v37
	v_max_f32_e32 v37, 0, v37
	v_sqrt_f32_e32 v37, v37
	v_add_f32_e32 v1, 1.0, v1
	v_rcp_f32_e32 v1, v1
	v_cmp_gt_i32_e32 vcc, s70, v108
	v_mul_f32_e32 v1, v1, v37
	s_nop 0
	v_cndmask_b32_e32 v36, 1.0, v36, vcc
	ds_write_b32 v142, v36 offset:50176
	v_add_u32_e32 v36, 0x14400, v142
	s_nop 0
	v_mul_f32_e32 v1, v192, v1
	v_cndmask_b32_e32 v1, 0, v1, vcc
	ds_write_b32 v36, v1
	v_add_f32_e32 v1, v52, v43
	v_mul_f32_e32 v1, 0xbfb8aa3b, v1
	v_exp_f32_e32 v1, v1
	s_nop 0
	v_add_f32_e32 v1, 1.0, v1
	v_rcp_f32_e32 v1, v1
	s_nop 0
	v_mul_f32_e32 v1, v89, v1
	v_mul_f32_e32 v36, 0x3fb8aa3b, v1
	v_exp_f32_e32 v36, v36
	v_add_f32_e32 v38, v1, v1
	v_cmp_nlt_f32_e32 vcc, s33, v38
	s_and_saveexec_b64 s[6:7], vcc
	s_xor_b64 s[6:7], exec, s[6:7]
	v_fma_f32 v37, -v36, v36, 1.0
	s_andn2_saveexec_b64 s[6:7], s[6:7]
	v_fmamk_f32 v1, v38, 0x3d2aaaab, v225
	v_fma_f32 v1, v38, v1, 0.5
	v_fma_f32 v1, v38, v1, 1.0
	v_mul_f32_e64 v37, v1, -v38
	s_or_b64 exec, exec, s[6:7]
	v_add_f32_e32 v1, v53, v39
	v_mul_f32_e32 v1, 0xbfb8aa3b, v1
	v_exp_f32_e32 v1, v1
	v_max_f32_e32 v37, v37, v37
	v_max_f32_e32 v37, 0, v37
	v_sqrt_f32_e32 v37, v37
	v_add_f32_e32 v1, 1.0, v1
	v_rcp_f32_e32 v1, v1
	v_cmp_gt_i32_e32 vcc, s70, v109
	v_mul_f32_e32 v1, v1, v37
	ds_read_b32 v37, v143 offset:17408
	v_cndmask_b32_e32 v36, 1.0, v36, vcc
	ds_write_b32 v143, v36 offset:50176
	v_add_u32_e32 v36, 0x14400, v143
	s_nop 0
	s_waitcnt lgkmcnt(1)
	v_mul_f32_e32 v1, v37, v1
	v_cndmask_b32_e32 v1, 0, v1, vcc
	ds_write_b32 v36, v1
	s_waitcnt lgkmcnt(0)
	s_barrier
	s_and_saveexec_b64 s[6:7], s[36:37]
	s_cbranch_execz .LBB0_1353
	s_mov_b32 s43, 0

.LBB0_1370:
	v_add_u32_e32 v1, s64, v93
	ds_read_b32 v1, v1
	s_add_u32 s43, s7, s23
	v_lshlrev_b32_e32 v36, 16, v87
	s_addc_u32 s59, s6, s83
	s_mulk_i32 s59, 0x3000
	s_waitcnt lgkmcnt(0)
	v_mul_f32_e32 v1, v1, v36
	v_mad_u64_u32 v[36:37], vcc, s43, v230, v[50:51]
	v_cvt_pk_bf16_f32 v1, v1, s0
	v_add_u32_e32 v37, s59, v37
	global_store_short v[36:37], v1, off
	s_cmp_ge_i32 s19, s70
	s_cbranch_scc1 .LBB0_1355
.LBB0_1371:
	v_add_u32_e32 v1, s65, v93
	ds_read_b32 v1, v1
	s_add_u32 s43, s7, s19
	v_lshlrev_b32_e32 v36, 16, v84
	s_addc_u32 s59, s6, s84
	s_mulk_i32 s59, 0x3000
	s_waitcnt lgkmcnt(0)
	v_mul_f32_e32 v1, v1, v36
	v_mad_u64_u32 v[36:37], vcc, s43, v230, v[50:51]
	v_cvt_pk_bf16_f32 v1, v1, s0
	v_add_u32_e32 v37, s59, v37
	global_store_short v[36:37], v1, off
	s_cmp_ge_i32 s20, s70
	s_cbranch_scc1 .LBB0_1356
.LBB0_1372:
	v_add_u32_e32 v1, s66, v93
	ds_read_b32 v1, v1
	s_add_u32 s43, s7, s20
	v_lshlrev_b32_e32 v36, 16, v86
	s_addc_u32 s59, s6, s85
	s_mulk_i32 s59, 0x3000
	s_waitcnt lgkmcnt(0)
	v_mul_f32_e32 v1, v1, v36
	v_mad_u64_u32 v[36:37], vcc, s43, v230, v[50:51]
	v_cvt_pk_bf16_f32 v1, v1, s0
	v_add_u32_e32 v37, s59, v37
	global_store_short v[36:37], v1, off
	s_cmp_ge_i32 s21, s70
	s_cbranch_scc1 .LBB0_1357
.LBB0_1373:
	v_add_u32_e32 v1, s67, v93
	ds_read_b32 v1, v1
	s_add_u32 s43, s7, s21
	v_lshlrev_b32_e32 v36, 16, v81
	s_addc_u32 s59, s6, s86
	s_mulk_i32 s59, 0x3000
	s_waitcnt lgkmcnt(0)
	v_mul_f32_e32 v1, v1, v36
	v_mad_u64_u32 v[36:37], vcc, s43, v230, v[50:51]
	v_cvt_pk_bf16_f32 v1, v1, s0
	v_add_u32_e32 v37, s59, v37
	global_store_short v[36:37], v1, off
	s_cmp_ge_i32 s24, s70
	s_cbranch_scc1 .LBB0_1358
.LBB0_1374:
	v_add_u32_e32 v1, s68, v93
	ds_read_b32 v1, v1
	s_add_u32 s43, s7, s24
	v_lshlrev_b32_e32 v36, 16, v85
	s_addc_u32 s59, s6, s87
	s_mulk_i32 s59, 0x3000
	s_waitcnt lgkmcnt(0)
	v_mul_f32_e32 v1, v1, v36
	v_mad_u64_u32 v[36:37], vcc, s43, v230, v[50:51]
	v_cvt_pk_bf16_f32 v1, v1, s0
	v_add_u32_e32 v37, s59, v37
	global_store_short v[36:37], v1, off
	s_cmp_ge_i32 s25, s70
	s_cbranch_scc1 .LBB0_1359
.LBB0_1375:
	v_add_u32_e32 v1, s69, v93
	ds_read_b32 v1, v1
	s_add_u32 s43, s7, s25
	v_lshlrev_b32_e32 v36, 16, v79
	s_addc_u32 s59, s6, s88
	s_mulk_i32 s59, 0x3000
	s_waitcnt lgkmcnt(0)
	v_mul_f32_e32 v1, v1, v36
	v_mad_u64_u32 v[36:37], vcc, s43, v230, v[50:51]
	v_cvt_pk_bf16_f32 v1, v1, s0
	v_add_u32_e32 v37, s59, v37
	global_store_short v[36:37], v1, off
	s_cmp_ge_i32 s26, s70
	s_cbranch_scc1 .LBB0_1360
.LBB0_1376:
	v_add_u32_e32 v1, s73, v93
	ds_read_b32 v1, v1
	s_add_u32 s43, s7, s26
	v_lshlrev_b32_e32 v36, 16, v83
	s_addc_u32 s59, s6, s89
	s_mulk_i32 s59, 0x3000
	s_waitcnt lgkmcnt(0)
	v_mul_f32_e32 v1, v1, v36
	v_mad_u64_u32 v[36:37], vcc, s43, v230, v[50:51]
	v_cvt_pk_bf16_f32 v1, v1, s0
	v_add_u32_e32 v37, s59, v37
	global_store_short v[36:37], v1, off
	s_cmp_ge_i32 s27, s70
	s_cbranch_scc1 .LBB0_1361
.LBB0_1377:
	v_add_u32_e32 v1, s74, v93
	ds_read_b32 v1, v1
	s_add_u32 s43, s7, s27
	v_lshlrev_b32_e32 v36, 16, v77
	s_addc_u32 s59, s6, s90
	s_mulk_i32 s59, 0x3000
	s_waitcnt lgkmcnt(0)
	v_mul_f32_e32 v1, v1, v36
	v_mad_u64_u32 v[36:37], vcc, s43, v230, v[50:51]
	v_cvt_pk_bf16_f32 v1, v1, s0
	v_add_u32_e32 v37, s59, v37
	global_store_short v[36:37], v1, off
	s_cmp_ge_i32 s28, s70
	s_cbranch_scc1 .LBB0_1362
.LBB0_1378:
	v_add_u32_e32 v1, s75, v93
	ds_read_b32 v1, v1
	s_add_u32 s43, s7, s28
	v_lshlrev_b32_e32 v36, 16, v80
	s_addc_u32 s59, s6, s91
	s_mulk_i32 s59, 0x3000
	s_waitcnt lgkmcnt(0)
	v_mul_f32_e32 v1, v1, v36
	v_mad_u64_u32 v[36:37], vcc, s43, v230, v[50:51]
	v_cvt_pk_bf16_f32 v1, v1, s0
	v_add_u32_e32 v37, s59, v37
	global_store_short v[36:37], v1, off
	s_cmp_ge_i32 s29, s70
	s_cbranch_scc1 .LBB0_1363
.LBB0_1379:
	v_add_u32_e32 v1, s76, v93
	ds_read_b32 v1, v1
	s_add_u32 s43, s7, s29
	v_lshlrev_b32_e32 v36, 16, v75
	s_addc_u32 s59, s6, s92
	s_mulk_i32 s59, 0x3000
	s_waitcnt lgkmcnt(0)
	v_mul_f32_e32 v1, v1, v36
	v_mad_u64_u32 v[36:37], vcc, s43, v230, v[50:51]
	v_cvt_pk_bf16_f32 v1, v1, s0
	v_add_u32_e32 v37, s59, v37
	global_store_short v[36:37], v1, off
	s_cmp_ge_i32 s30, s70
	s_cbranch_scc1 .LBB0_1364
.LBB0_1380:
	v_add_u32_e32 v1, s77, v93
	ds_read_b32 v1, v1
	s_add_u32 s43, s7, s30
	v_lshlrev_b32_e32 v36, 16, v78
	s_addc_u32 s59, s6, s93
	s_mulk_i32 s59, 0x3000
	s_waitcnt lgkmcnt(0)
	v_mul_f32_e32 v1, v1, v36
	v_mad_u64_u32 v[36:37], vcc, s43, v230, v[50:51]
	v_cvt_pk_bf16_f32 v1, v1, s0
	v_add_u32_e32 v37, s59, v37
	global_store_short v[36:37], v1, off
	s_cmp_ge_i32 s31, s70
	s_cbranch_scc1 .LBB0_1365
.LBB0_1381:
	v_add_u32_e32 v1, s78, v93
	ds_read_b32 v1, v1
	s_add_u32 s43, s7, s31
	v_lshlrev_b32_e32 v36, 16, v73
	s_addc_u32 s59, s6, s94
	s_mulk_i32 s59, 0x3000
	s_waitcnt lgkmcnt(0)
	v_mul_f32_e32 v1, v1, v36
	v_mad_u64_u32 v[36:37], vcc, s43, v230, v[50:51]
	v_cvt_pk_bf16_f32 v1, v1, s0
	v_add_u32_e32 v37, s59, v37
	global_store_short v[36:37], v1, off
	s_cmp_ge_i32 s34, s70
	s_cbranch_scc1 .LBB0_1366
.LBB0_1382:
	v_add_u32_e32 v1, s79, v93
	ds_read_b32 v1, v1
	s_add_u32 s43, s7, s34
	v_lshlrev_b32_e32 v36, 16, v76
	s_addc_u32 s59, s6, s95
	s_mulk_i32 s59, 0x3000
	s_waitcnt lgkmcnt(0)
	v_mul_f32_e32 v1, v1, v36
	v_mad_u64_u32 v[36:37], vcc, s43, v230, v[50:51]
	v_cvt_pk_bf16_f32 v1, v1, s0
	v_add_u32_e32 v37, s59, v37
	global_store_short v[36:37], v1, off
	s_cmp_ge_i32 s35, s70
	s_cbranch_scc1 .LBB0_1367
.LBB0_1383:
	v_add_u32_e32 v1, s80, v93
	ds_read_b32 v1, v1
	s_add_u32 s43, s7, s35
	v_lshlrev_b32_e32 v36, 16, v72
	s_addc_u32 s59, s6, s96
	s_mulk_i32 s59, 0x3000
	s_waitcnt lgkmcnt(0)
	v_mul_f32_e32 v1, v1, v36
	v_mad_u64_u32 v[36:37], vcc, s43, v230, v[50:51]
	v_cvt_pk_bf16_f32 v1, v1, s0
	v_add_u32_e32 v37, s59, v37
	global_store_short v[36:37], v1, off
	s_cmp_ge_i32 s60, s70
	s_cbranch_scc1 .LBB0_1368
.LBB0_1384:
	v_add_u32_e32 v1, s81, v93
	ds_read_b32 v1, v1
	s_add_u32 s43, s7, s60
	v_lshlrev_b32_e32 v36, 16, v74
	s_addc_u32 s59, s6, s97
	s_mulk_i32 s59, 0x3000
	s_waitcnt lgkmcnt(0)
	v_mul_f32_e32 v1, v1, v36
	v_mad_u64_u32 v[36:37], vcc, s43, v230, v[50:51]
	v_cvt_pk_bf16_f32 v1, v1, s0
	v_add_u32_e32 v37, s59, v37
	global_store_short v[36:37], v1, off
	s_cmp_ge_i32 s61, s70
	s_cbranch_scc1 .LBB0_1369
.LBB0_1385:
	v_add_u32_e32 v1, s82, v93
	ds_read_b32 v1, v1
	s_add_u32 s7, s7, s61
	v_lshlrev_b32_e32 v36, 16, v71
	s_addc_u32 s6, s6, s62
	s_mul_i32 s43, s6, 0x3000
	s_waitcnt lgkmcnt(0)
	v_mul_f32_e32 v1, v1, v36
	v_mad_u64_u32 v[36:37], s[6:7], s7, v230, v[50:51]
	v_cvt_pk_bf16_f32 v1, v1, s0
	v_add_u32_e32 v37, s43, v37
	global_store_short v[36:37], v1, off
	s_cmp_eq_u32 s72, s63
	s_cbranch_scc1 .LBB0_1402

.LBB0_1387:
	s_add_u32 vcc_lo, s6, s23
	s_addc_u32 vcc_hi, s7, s83
	s_lshl_b64 vcc, vcc, 12
	v_lshl_add_u64 v[36:37], v[48:49], 0, vcc
	global_load_ushort v150, v[36:37], off
	s_cmp_ge_i32 s19, s43
	s_cbranch_scc1 .LBB0_1271
.LBB0_1388:
	s_add_u32 vcc_lo, s6, s19
	s_addc_u32 vcc_hi, s7, s84
	s_lshl_b64 vcc, vcc, 12
	v_lshl_add_u64 v[36:37], v[48:49], 0, vcc
	global_load_ushort v149, v[36:37], off
	v_mov_b32_e32 v151, 0
	s_cmp_ge_i32 s20, s43
	v_mov_b32_e32 v152, 0
	s_cbranch_scc1 .LBB0_1272
.LBB0_1389:
	s_add_u32 vcc_lo, s6, s20
	s_addc_u32 vcc_hi, s7, s85
	s_lshl_b64 vcc, vcc, 12
	v_lshl_add_u64 v[36:37], v[48:49], 0, vcc
	global_load_ushort v152, v[36:37], off
	s_cmp_ge_i32 s21, s43
	s_cbranch_scc1 .LBB0_1273
.LBB0_1390:
	s_add_u32 vcc_lo, s6, s21
	s_addc_u32 vcc_hi, s7, s86
	s_lshl_b64 vcc, vcc, 12
	v_lshl_add_u64 v[36:37], v[48:49], 0, vcc
	global_load_ushort v151, v[36:37], off
	v_mov_b32_e32 v153, 0
	s_cmp_ge_i32 s24, s43
	v_mov_b32_e32 v154, 0
	s_cbranch_scc1 .LBB0_1274
.LBB0_1391:
	s_add_u32 vcc_lo, s6, s24
	s_addc_u32 vcc_hi, s7, s87
	s_lshl_b64 vcc, vcc, 12
	v_lshl_add_u64 v[36:37], v[48:49], 0, vcc
	global_load_ushort v154, v[36:37], off
	s_cmp_ge_i32 s25, s43
	s_cbranch_scc1 .LBB0_1275
.LBB0_1392:
	s_add_u32 vcc_lo, s6, s25
	s_addc_u32 vcc_hi, s7, s88
	s_lshl_b64 vcc, vcc, 12
	v_lshl_add_u64 v[36:37], v[48:49], 0, vcc
	global_load_ushort v153, v[36:37], off
	v_mov_b32_e32 v155, 0
	s_cmp_ge_i32 s26, s43
	v_mov_b32_e32 v156, 0
	s_cbranch_scc1 .LBB0_1276
.LBB0_1393:
	s_add_u32 vcc_lo, s6, s26
	s_addc_u32 vcc_hi, s7, s89
	s_lshl_b64 vcc, vcc, 12
	v_lshl_add_u64 v[36:37], v[48:49], 0, vcc
	global_load_ushort v156, v[36:37], off
	s_cmp_ge_i32 s27, s43
	s_cbranch_scc1 .LBB0_1277
.LBB0_1394:
	s_add_u32 vcc_lo, s6, s27
	s_addc_u32 vcc_hi, s7, s90
	s_lshl_b64 vcc, vcc, 12
	v_lshl_add_u64 v[36:37], v[48:49], 0, vcc
	global_load_ushort v155, v[36:37], off
	v_mov_b32_e32 v157, 0
	s_cmp_ge_i32 s28, s43
	v_mov_b32_e32 v158, 0
	s_cbranch_scc1 .LBB0_1278
.LBB0_1395:
	s_add_u32 vcc_lo, s6, s28
	s_addc_u32 vcc_hi, s7, s91
	s_lshl_b64 vcc, vcc, 12
	v_lshl_add_u64 v[36:37], v[48:49], 0, vcc
	global_load_ushort v158, v[36:37], off
	s_cmp_ge_i32 s29, s43
	s_cbranch_scc1 .LBB0_1279
.LBB0_1396:
	s_add_u32 vcc_lo, s6, s29
	s_addc_u32 vcc_hi, s7, s92
	s_lshl_b64 vcc, vcc, 12
	v_lshl_add_u64 v[36:37], v[48:49], 0, vcc
	global_load_ushort v157, v[36:37], off
	v_mov_b32_e32 v159, 0
	s_cmp_ge_i32 s30, s43
	v_mov_b32_e32 v160, 0
	s_cbranch_scc1 .LBB0_1280
.LBB0_1397:
	s_add_u32 vcc_lo, s6, s30
	s_addc_u32 vcc_hi, s7, s93
	s_lshl_b64 vcc, vcc, 12
	v_lshl_add_u64 v[36:37], v[48:49], 0, vcc
	global_load_ushort v160, v[36:37], off
	s_cmp_ge_i32 s31, s43
	s_cbranch_scc1 .LBB0_1281
.LBB0_1398:
	s_add_u32 vcc_lo, s6, s31
	s_addc_u32 vcc_hi, s7, s94
	s_lshl_b64 vcc, vcc, 12
	v_lshl_add_u64 v[36:37], v[48:49], 0, vcc
	global_load_ushort v159, v[36:37], off
	v_mov_b32_e32 v161, 0
	s_cmp_ge_i32 s34, s43
	v_mov_b32_e32 v162, 0
	s_cbranch_scc1 .LBB0_1282
.LBB0_1399:
	s_add_u32 vcc_lo, s6, s34
	s_addc_u32 vcc_hi, s7, s95
	s_lshl_b64 vcc, vcc, 12
	v_lshl_add_u64 v[36:37], v[48:49], 0, vcc
	global_load_ushort v162, v[36:37], off
	s_cmp_ge_i32 s35, s43
	s_cbranch_scc1 .LBB0_1283
.LBB0_1400:
	s_add_u32 vcc_lo, s6, s35
	s_addc_u32 vcc_hi, s7, s96
	s_lshl_b64 vcc, vcc, 12
	v_lshl_add_u64 v[36:37], v[48:49], 0, vcc
	global_load_ushort v161, v[36:37], off
	v_mov_b32_e32 v163, 0
	s_cmp_ge_i32 s60, s43
	v_mov_b32_e32 v172, 0
	s_cbranch_scc1 .LBB0_1284
.LBB0_1401:
	s_add_u32 vcc_lo, s6, s60
	s_addc_u32 vcc_hi, s7, s97
	s_lshl_b64 vcc, vcc, 12
	v_lshl_add_u64 v[36:37], v[48:49], 0, vcc
	global_load_ushort v172, v[36:37], off
	s_cmp_ge_i32 s61, s43
	s_cbranch_scc0 .LBB0_1285
	s_branch .LBB0_1286
.LBB0_1402:
	s_and_saveexec_b64 s[6:7], s[36:37]
	s_cbranch_execz .LBB0_914
	s_mul_i32 s8, s13, 0x6000
	s_mul_hi_u32 s9, s12, 0x6000
	v_readlane_b32 s60, v248, 52
	s_add_i32 s9, s9, s8
	s_mul_i32 s8, s12, 0x6000
	v_readlane_b32 s74, v249, 2
	v_readlane_b32 s75, v249, 3
	s_add_u32 s8, s74, s8
	s_addc_u32 s9, s75, s9
	s_lshl_b32 s12, s14, 2
	s_add_u32 s8, s8, s12
	s_addc_u32 s9, s9, 0
	s_add_u32 s8, s8, s16
	s_addc_u32 s9, s9, s17
	s_lshl_b64 s[10:11], s[10:11], 2
	s_add_u32 s10, s74, s10
	s_addc_u32 s11, s75, s11
	s_add_u32 s10, s10, s16
	s_addc_u32 s11, s11, s17
	s_add_i32 s12, s15, s22
	global_store_dword v44, v59, s[10:11]
	s_add_i32 s10, s12, -3
	s_ashr_i32 s11, s10, 31
	s_lshl_b64 s[10:11], s[10:11], 13
	v_lshl_add_u64 v[2:3], v[46:47], 0, s[10:11]
	global_load_dword v1, v[2:3], off
	s_waitcnt vmcnt(0)
	v_mov_b32_e32 v45, v34
	v_lshl_add_u64 v[4:5], s[8:9], 0, v[44:45]
	v_readlane_b32 s61, v248, 53
	v_readlane_b32 s62, v248, 54
	v_readlane_b32 s63, v248, 55
	v_readlane_b32 s64, v248, 56
	v_readlane_b32 s65, v248, 57
	v_readlane_b32 s66, v248, 58
	v_readlane_b32 s67, v248, 59
	v_readlane_b32 s68, v248, 60
	v_readlane_b32 s69, v248, 61
	v_readlane_b32 s70, v248, 62
	v_readlane_b32 s71, v248, 63
	v_readlane_b32 s72, v249, 0
	v_readlane_b32 s73, v249, 1
	s_waitcnt lgkmcnt(0)
	global_store_dword v44, v1, s[8:9]
	s_movk_i32 s8, 0x2000
	v_add_co_u32_e32 v2, vcc, s8, v2
	s_add_i32 s8, s12, -1
	s_nop 0
	v_addc_co_u32_e32 v3, vcc, 0, v3, vcc
	global_load_dword v1, v[2:3], off
	v_add_co_u32_e32 v2, vcc, 0x2000, v4
	s_ashr_i32 s9, s8, 31
	s_nop 0
	v_addc_co_u32_e32 v3, vcc, 0, v5, vcc
	s_lshl_b64 s[8:9], s[8:9], 13
	s_waitcnt vmcnt(0) lgkmcnt(0)
	global_store_dword v[2:3], v1, off
	v_lshl_add_u64 v[2:3], v[46:47], 0, s[8:9]
	global_load_dword v1, v[2:3], off
	v_add_co_u32_e32 v2, vcc, 0x4000, v4
	s_nop 1
	v_addc_co_u32_e32 v3, vcc, 0, v5, vcc
	s_waitcnt vmcnt(0) lgkmcnt(0)
	global_store_dword v[2:3], v1, off
	s_branch .LBB0_914
